# hand-written pipelined row pass (residual + rmsnorm) for phases 4/7/16/19: 16-byte loads, all loads of a row in flight, next row prefetched, gains kept in registers
# speedup vs baseline: 1.0579x; 1.0579x over previous
; DI bf16* xb_row(float* outp, int m) { return (bf16*)((char*)outp + (size_t)m * 8192 + 4096); }
; template <bool XINB, bool XOUTB> DI void row_resid_norm(const bf16* trow, const bf16* trow2, int npart, const void* xin, void* xout, const float* gpost, float* rstd_out, int lane) {
;   const u32x2* tr = (const u32x2*)trow + lane; const u32x2* tr2 = (const u32x2*)trow2 + lane; const f32x4* gr = (const f32x4*)gpost + lane;
; __global__ void __launch_bounds__(512) fwd_mega(Args a_) {
;     ...
;     } else if (ph == 19) {
;       for (int m = gw; m < MT; m += NGW)
;         row_resid_norm<true, false>((const bf16*)(ws + A_T) + (size_t)m * DM, tail8 ? (const bf16*)(ws + A_PF) + (size_t)(m - NPR) * DM : (const bf16*)(ws + A_H) + (size_t)m * DM, tail8 ? (m < NPR ? 0 : 8) : 1, xb_row(outp, m), outp + (size_t)m * DM, a.in[9] + DM, nullptr, lane);
.LBB0_64:
	s_ashr_i32 s0, s0, 6
	s_waitcnt lgkmcnt(0)
	s_add_u32 s96, s54, 0x2a210000
	v_writelane_b32 v255, s0, 36
	s_addc_u32 s97, s55, 0
	v_and_b32_e32 v186, 63, v184
	v_ashrrev_i32_e32 v185, 31, v184
	s_andn2_b64 vcc, exec, s[10:11]
	s_mov_b64 s[6:7], -1
	s_cbranch_vccz .LBB0_452
	v_readlane_b32 s0, v255, 36
	s_add_i32 s72, s0, s81
	v_readlane_b32 s0, v255, 35
	s_cmp_lt_i32 s0, 7
	v_lshl_add_u64 v[188:189], s[60:61], 0, v[184:185]
	s_mov_b64 s[8:9], -1
	s_mov_b64 s[46:47], 0
	s_cbranch_scc1 .LBB0_122
	s_cmp_gt_i32 s0, 15
	s_mov_b64 s[6:7], 0
	s_cbranch_scc0 .LBB0_167
	v_readlane_b32 s0, v255, 35
	s_cmp_gt_i32 s0, 18
	s_cbranch_scc0 .LBB0_127
	s_cmp_eq_u32 s0, 19
	s_mov_b64 s[6:7], -1
	s_cbranch_scc0 .LBB0_126
	s_cmpk_gt_i32 s72, 0x43ff
	s_cbranch_scc1 .LBB0_125
	s_and_b64 vcc, exec, s[78:79]
	s_cbranch_vccz .Lrp_orig19
	s_load_dwordx2 s[6:7], s[22:23], 0x48
	s_mov_b32 s10, 0x21000000
	s_mov_b32 s11, 1
	s_waitcnt lgkmcnt(0)
	s_add_u32 s6, s6, 0x2000
	s_addc_u32 s7, s7, 0
	s_branch .Lrp_entry
.Lrp_orig19:
	s_load_dwordx2 s[2:3], s[22:23], 0x48
	v_lshlrev_b32_e32 v112, 4, v186
	s_add_u32 s0, s54, 0x21000000
	s_addc_u32 s1, s55, 0
	s_ashr_i32 s73, s72, 31
	s_waitcnt lgkmcnt(0)
	v_lshl_add_u64 v[0:1], s[2:3], 0, v[112:113]
	s_mov_b64 s[2:3], 0x2000
	v_lshl_add_u64 v[32:33], v[0:1], 0, s[2:3]
	s_mov_b64 s[2:3], 0x3000
	v_lshl_add_u64 v[34:35], v[0:1], 0, s[2:3]
	s_mov_b64 s[2:3], 0x3400
	v_lshl_add_u64 v[36:37], v[0:1], 0, s[2:3]
	s_mov_b64 s[2:3], 0x3800
	v_lshl_add_u64 v[38:39], v[0:1], 0, s[2:3]
	s_mov_b64 s[2:3], 0x3c00
	v_lshl_add_u64 v[40:41], v[0:1], 0, s[2:3]
	s_lshl_b64 s[2:3], s[72:73], 13
	s_add_u32 s6, s52, s2
	s_addc_u32 s7, s53, s3
	s_lshl_b64 s[2:3], s[72:73], 12
	s_add_u32 s2, s54, s2
	s_addc_u32 s3, s55, s3
	s_add_u32 s8, s2, 0x7400000
	v_lshlrev_b32_e32 v42, 3, v186
	v_mov_b32_e32 v43, v113
	s_addc_u32 s9, s3, 0
	v_lshlrev_b32_e32 v44, 3, v186
	v_mov_b32_e32 v45, v113
	s_mov_b32 s2, s72
	s_branch .LBB0_72

; DI float bflo(unsigned w) { return __uint_as_float(w << 16); }
; DI float bfhi(unsigned w) { return __uint_as_float(w & 0xffff0000u); }
; template <bool XINB, bool XOUTB> DI void row_resid_norm(const bf16* trow, const bf16* trow2, int npart, const void* xin, void* xout, const float* gpost, float* rstd_out, int lane) {
;   const u32x2* tr = (const u32x2*)trow + lane; const u32x2* tr2 = (const u32x2*)trow2 + lane; const f32x4* gr = (const f32x4*)gpost + lane;
;   f32x4 t[8], x[8]; float s = 0.f;
; #pragma unroll
;   for (int j = 0; j < 8; ++j) {
;     if (npart == 8) { f32x4 acc4 = {0.f, 0.f, 0.f, 0.f};
; #pragma unroll
;       for (int p = 0; p < 8; ++p) { const u32x2 w = (tr2 + (size_t)p * (1024 * 2048 / 4))[64 * j]; acc4 += (f32x4){bflo(w.x), bfhi(w.x), bflo(w.y), bfhi(w.y)}; }
;       t[j] = acc4;
;     } else { const u32x2 w = tr[64 * j]; u32x2 w2 = {0u, 0u}; if (npart == 1) w2 = tr2[64 * j]; t[j] = (f32x4){bflo(w.x) + bflo(w2.x), bfhi(w.x) + bfhi(w2.x), bflo(w.y) + bflo(w2.y), bfhi(w.y) + bfhi(w2.y)}; }
;     s += (t[j].x * t[j].x + t[j].y * t[j].y) + (t[j].z * t[j].z + t[j].w * t[j].w); }
; #pragma unroll
;   for (int j = 0; j < 8; ++j) { if (XINB) { const u32x2 w = ((const u32x2*)xin + lane)[64 * j]; x[j] = (f32x4){bflo(w.x), bfhi(w.x), bflo(w.y), bfhi(w.y)}; } else x[j] = ((const f32x4*)xin + lane)[64 * j]; }
.Lrp_entry:
	v_lshlrev_b32_e32 v162, 4, v186
	v_lshlrev_b32_e32 v163, 5, v186
	s_lshl_b32 s0, s72, 12
	s_add_u32 s0, s0, 0xb800000
	s_add_u32 s0, s54, s0
	s_addc_u32 s1, s55, 0
	s_lshl_b32 s2, s72, 13
	s_add_u32 s2, s2, 0x1000
	s_add_u32 s2, s52, s2
	s_addc_u32 s3, s53, 0
	s_mov_b64 s[4:5], s[2:3]
	s_lshl_b32 s8, s72, 2
	s_add_u32 s8, s8, 0x2a210000
	s_add_u32 s8, s54, s8
	s_addc_u32 s9, s55, 0
	s_add_u32 s12, s6, 0x1000
	s_addc_u32 s13, s7, 0
	global_load_dwordx4 v[0:3], v163, s[6:7] offset:0
	global_load_dwordx4 v[4:7], v163, s[6:7] offset:16
	global_load_dwordx4 v[8:11], v163, s[6:7] offset:2048
	global_load_dwordx4 v[12:15], v163, s[6:7] offset:2064
	global_load_dwordx4 v[16:19], v163, s[12:13] offset:0
	global_load_dwordx4 v[20:23], v163, s[12:13] offset:16
	global_load_dwordx4 v[24:27], v163, s[12:13] offset:2048
	global_load_dwordx4 v[28:31], v163, s[12:13] offset:2064
	global_load_dwordx4 v[64:67], v162, s[0:1] offset:0
	global_load_dwordx4 v[68:71], v162, s[0:1] offset:1024
	global_load_dwordx4 v[72:75], v162, s[0:1] offset:2048
	global_load_dwordx4 v[76:79], v162, s[0:1] offset:3072
	global_load_dwordx4 v[80:83], v162, s[2:3] offset:0
	global_load_dwordx4 v[84:87], v162, s[2:3] offset:1024
	global_load_dwordx4 v[88:91], v162, s[2:3] offset:2048
	global_load_dwordx4 v[92:95], v162, s[2:3] offset:3072
	s_mov_b32 s6, 0
.Lrp_loop:
	s_cmp_eq_u32 s6, 0
	s_cbranch_scc1 .Lrp_w0
	s_bitcmp1_b32 s11, 0
	s_cbranch_scc1 .Lrp_w8
	s_waitcnt vmcnt(5)
	s_branch .Lrp_wd
.Lrp_w8:
	s_waitcnt vmcnt(8)
	s_branch .Lrp_wd

; DI float bflo(unsigned w) { return __uint_as_float(w << 16); }
; DI float bfhi(unsigned w) { return __uint_as_float(w & 0xffff0000u); }
; DI float wave_sum(float v) {
;   v += __int_as_float(__builtin_amdgcn_ds_swizzle(__float_as_int(v), (1 << 10) | 0x1f));
;   v += __int_as_float(__builtin_amdgcn_ds_swizzle(__float_as_int(v), (2 << 10) | 0x1f));
;   v += __int_as_float(__builtin_amdgcn_ds_swizzle(__float_as_int(v), (4 << 10) | 0x1f));
;   v += __int_as_float(__builtin_amdgcn_ds_swizzle(__float_as_int(v), (8 << 10) | 0x1f));
;   v += __int_as_float(__builtin_amdgcn_ds_swizzle(__float_as_int(v), (16 << 10) | 0x1f));
; template <bool XINB, bool XOUTB> DI void row_resid_norm(const bf16* trow, const bf16* trow2, int npart, const void* xin, void* xout, const float* gpost, float* rstd_out, int lane) {
;     ...
; #pragma unroll
;   for (int j = 0; j < 8; ++j) {
;     if (npart == 8) { f32x4 acc4 = {0.f, 0.f, 0.f, 0.f};
; #pragma unroll
;       for (int p = 0; p < 8; ++p) { const u32x2 w = (tr2 + (size_t)p * (1024 * 2048 / 4))[64 * j]; acc4 += (f32x4){bflo(w.x), bfhi(w.x), bflo(w.y), bfhi(w.y)}; }
;       t[j] = acc4;
;     } else { const u32x2 w = tr[64 * j]; u32x2 w2 = {0u, 0u}; if (npart == 1) w2 = tr2[64 * j]; t[j] = (f32x4){bflo(w.x) + bflo(w2.x), bfhi(w.x) + bfhi(w2.x), bflo(w.y) + bflo(w2.y), bfhi(w.y) + bfhi(w2.y)}; }
;     s += (t[j].x * t[j].x + t[j].y * t[j].y) + (t[j].z * t[j].z + t[j].w * t[j].w); }
; #pragma unroll
;   for (int j = 0; j < 8; ++j) { if (XINB) { const u32x2 w = ((const u32x2*)xin + lane)[64 * j]; x[j] = (f32x4){bflo(w.x), bfhi(w.x), bflo(w.y), bfhi(w.y)}; } else x[j] = ((const f32x4*)xin + lane)[64 * j]; }
;   const float rstd = rsqrtf(wave_sum(s) * (1.f / DM) + EPS);
.Lrp_wd:
	v_mov_b32_e32 v32, v64
	v_mov_b32_e32 v33, v65
	v_mov_b32_e32 v34, v66
	v_mov_b32_e32 v35, v67
	v_mov_b32_e32 v36, v68
	v_mov_b32_e32 v37, v69
	v_mov_b32_e32 v38, v70
	v_mov_b32_e32 v39, v71
	v_mov_b32_e32 v40, v72
	v_mov_b32_e32 v41, v73
	v_mov_b32_e32 v42, v74
	v_mov_b32_e32 v43, v75
	v_mov_b32_e32 v44, v76
	v_mov_b32_e32 v45, v77
	v_mov_b32_e32 v46, v78
	v_mov_b32_e32 v47, v79
	v_mov_b32_e32 v48, v80
	v_mov_b32_e32 v49, v81
	v_mov_b32_e32 v50, v82
	v_mov_b32_e32 v51, v83
	v_mov_b32_e32 v52, v84
	v_mov_b32_e32 v53, v85
	v_mov_b32_e32 v54, v86
	v_mov_b32_e32 v55, v87
	v_mov_b32_e32 v56, v88
	v_mov_b32_e32 v57, v89
	v_mov_b32_e32 v58, v90
	v_mov_b32_e32 v59, v91
	v_mov_b32_e32 v60, v92
	v_mov_b32_e32 v61, v93
	v_mov_b32_e32 v62, v94
	v_mov_b32_e32 v63, v95
	s_cmp_eq_u32 s6, 7
	s_cbranch_scc1 .Lrp_nopref
	s_add_u32 s0, s0, 0x800000
	s_addc_u32 s1, s1, 0
	s_add_u32 s2, s2, 0x1000000
	s_addc_u32 s3, s3, 0
	global_load_dwordx4 v[64:67], v162, s[0:1] offset:0
	global_load_dwordx4 v[68:71], v162, s[0:1] offset:1024
	global_load_dwordx4 v[72:75], v162, s[0:1] offset:2048
	global_load_dwordx4 v[76:79], v162, s[0:1] offset:3072
	global_load_dwordx4 v[80:83], v162, s[2:3] offset:0
	global_load_dwordx4 v[84:87], v162, s[2:3] offset:1024
	global_load_dwordx4 v[88:91], v162, s[2:3] offset:2048
	global_load_dwordx4 v[92:95], v162, s[2:3] offset:3072
.Lrp_nopref:
	v_lshlrev_b32_e32 v96, 16, v32
	v_and_b32_e32 v97, 0xffff0000, v32
	v_lshlrev_b32_e32 v98, 16, v33
	v_and_b32_e32 v99, 0xffff0000, v33
	v_lshlrev_b32_e32 v100, 16, v34
	v_and_b32_e32 v101, 0xffff0000, v34
	v_lshlrev_b32_e32 v102, 16, v35
	v_and_b32_e32 v103, 0xffff0000, v35
	v_lshlrev_b32_e32 v104, 16, v36
	v_and_b32_e32 v105, 0xffff0000, v36
	v_lshlrev_b32_e32 v106, 16, v37
	v_and_b32_e32 v107, 0xffff0000, v37
	v_lshlrev_b32_e32 v108, 16, v38
	v_and_b32_e32 v109, 0xffff0000, v38
	v_lshlrev_b32_e32 v110, 16, v39
	v_and_b32_e32 v111, 0xffff0000, v39
	v_lshlrev_b32_e32 v114, 16, v40
	v_and_b32_e32 v115, 0xffff0000, v40
	v_lshlrev_b32_e32 v116, 16, v41
	v_and_b32_e32 v117, 0xffff0000, v41
	v_lshlrev_b32_e32 v118, 16, v42
	v_and_b32_e32 v119, 0xffff0000, v42
	v_lshlrev_b32_e32 v120, 16, v43
	v_and_b32_e32 v121, 0xffff0000, v43
	v_lshlrev_b32_e32 v122, 16, v44
	v_and_b32_e32 v123, 0xffff0000, v44
	v_lshlrev_b32_e32 v124, 16, v45
	v_and_b32_e32 v125, 0xffff0000, v45
	v_lshlrev_b32_e32 v126, 16, v46
	v_and_b32_e32 v127, 0xffff0000, v46
	v_lshlrev_b32_e32 v128, 16, v47
	v_and_b32_e32 v129, 0xffff0000, v47
	v_mul_f32_e32 v168, v96, v96
	v_mul_f32_e32 v169, v97, v97
	v_mul_f32_e32 v170, v98, v98
	v_mul_f32_e32 v171, v99, v99
	v_fmac_f32_e32 v168, v100, v100
	v_fmac_f32_e32 v169, v101, v101
	v_fmac_f32_e32 v170, v102, v102
	v_fmac_f32_e32 v171, v103, v103
	v_fmac_f32_e32 v168, v104, v104
	v_fmac_f32_e32 v169, v105, v105
	v_fmac_f32_e32 v170, v106, v106
	v_fmac_f32_e32 v171, v107, v107
	v_fmac_f32_e32 v168, v108, v108
	v_fmac_f32_e32 v169, v109, v109
	v_fmac_f32_e32 v170, v110, v110
	v_fmac_f32_e32 v171, v111, v111
	v_fmac_f32_e32 v168, v114, v114
	v_fmac_f32_e32 v169, v115, v115
	v_fmac_f32_e32 v170, v116, v116
	v_fmac_f32_e32 v171, v117, v117
	v_fmac_f32_e32 v168, v118, v118
	v_fmac_f32_e32 v169, v119, v119
	v_fmac_f32_e32 v170, v120, v120
	v_fmac_f32_e32 v171, v121, v121
	v_fmac_f32_e32 v168, v122, v122
	v_fmac_f32_e32 v169, v123, v123
	v_fmac_f32_e32 v170, v124, v124
	v_fmac_f32_e32 v171, v125, v125
	v_fmac_f32_e32 v168, v126, v126
	v_fmac_f32_e32 v169, v127, v127
	v_fmac_f32_e32 v170, v128, v128
	v_fmac_f32_e32 v171, v129, v129
	v_add_f32_e32 v168, v168, v169
	v_add_f32_e32 v170, v170, v171
	v_add_f32_e32 v164, v168, v170
	v_lshlrev_b32_e32 v130, 16, v48
	v_and_b32_e32 v131, 0xffff0000, v48
	v_lshlrev_b32_e32 v132, 16, v49
	v_and_b32_e32 v133, 0xffff0000, v49
	v_lshlrev_b32_e32 v134, 16, v50
	v_and_b32_e32 v135, 0xffff0000, v50
	v_lshlrev_b32_e32 v136, 16, v51
	v_and_b32_e32 v137, 0xffff0000, v51
	v_lshlrev_b32_e32 v138, 16, v52
	v_and_b32_e32 v139, 0xffff0000, v52
	v_lshlrev_b32_e32 v140, 16, v53
	v_and_b32_e32 v141, 0xffff0000, v53
	v_lshlrev_b32_e32 v142, 16, v54
	v_and_b32_e32 v143, 0xffff0000, v54
	v_lshlrev_b32_e32 v144, 16, v55
	v_and_b32_e32 v145, 0xffff0000, v55
	v_lshlrev_b32_e32 v146, 16, v56
	v_and_b32_e32 v147, 0xffff0000, v56
	v_lshlrev_b32_e32 v148, 16, v57
	v_and_b32_e32 v149, 0xffff0000, v57
	v_lshlrev_b32_e32 v150, 16, v58
	v_and_b32_e32 v151, 0xffff0000, v58
	v_lshlrev_b32_e32 v152, 16, v59
	v_and_b32_e32 v153, 0xffff0000, v59
	v_lshlrev_b32_e32 v154, 16, v60
	v_and_b32_e32 v155, 0xffff0000, v60
	v_lshlrev_b32_e32 v156, 16, v61
	v_and_b32_e32 v157, 0xffff0000, v61
	v_lshlrev_b32_e32 v158, 16, v62
	v_and_b32_e32 v159, 0xffff0000, v62
	v_lshlrev_b32_e32 v160, 16, v63
	v_and_b32_e32 v161, 0xffff0000, v63
	ds_swizzle_b32 v165, v164 offset:swizzle(SWAP,1)
	s_waitcnt lgkmcnt(0)
	v_add_f32_e32 v164, v164, v165
	ds_swizzle_b32 v165, v164 offset:swizzle(SWAP,2)
	s_waitcnt lgkmcnt(0)
	v_add_f32_e32 v164, v164, v165
	ds_swizzle_b32 v165, v164 offset:swizzle(SWAP,4)
	s_waitcnt lgkmcnt(0)
	v_add_f32_e32 v164, v164, v165
	ds_swizzle_b32 v165, v164 offset:swizzle(SWAP,8)
	s_waitcnt lgkmcnt(0)
	v_add_f32_e32 v164, v164, v165
	ds_swizzle_b32 v165, v164 offset:swizzle(SWAP,16)
	s_waitcnt lgkmcnt(0)
; DI unsigned cvtpk(float lo, float hi) { unsigned r; asm volatile("v_cvt_pk_bf16_f32 %0, %1, %2" : "=v"(r) : "v"(lo), "v"(hi)); return r; }
; template <bool XINB, bool XOUTB> DI void row_resid_norm(const bf16* trow, const bf16* trow2, int npart, const void* xin, void* xout, const float* gpost, float* rstd_out, int lane) {
;     ...
;   const float rstd = rsqrtf(wave_sum(s) * (1.f / DM) + EPS);
;   float s2 = 0.f;
; #pragma unroll
;   for (int j = 0; j < 8; ++j) { const f32x4 gg = gr[64 * j]; x[j] = x[j] + t[j] * rstd * gg; s2 += (x[j].x * x[j].x + x[j].y * x[j].y) + (x[j].z * x[j].z + x[j].w * x[j].w); }
;   asm volatile("s_waitcnt vmcnt(0)" ::: "memory");
; #pragma unroll
;   for (int j = 0; j < 8; ++j) { if (XOUTB) { u32x2 w; w.x = cvtpk(x[j].x, x[j].y); w.y = cvtpk(x[j].z, x[j].w); ((u32x2*)xout + lane)[64 * j] = w; } else ((f32x4*)xout + lane)[64 * j] = x[j]; }
;   if (rstd_out) { const float rstd2 = rsqrtf(wave_sum(s2) * (1.f / DM) + EPS); if (lane == 0) *rstd_out = rstd2; }
	v_add_f32_e32 v164, v164, v165
	v_mov_b32_e32 v165, v164
	s_nop 1
	v_permlane32_swap_b32_e32 v164, v165
	v_add_f32_e32 v164, v164, v165
	v_fmamk_f32 v166, v164, 0x3a000000, v180
	v_rsq_f32_e32 v166, v166
	s_nop 0
	v_pk_mul_f32 v[96:97], v[96:97], v[166:167] op_sel_hi:[1,0]
	v_pk_mul_f32 v[98:99], v[98:99], v[166:167] op_sel_hi:[1,0]
	v_pk_mul_f32 v[100:101], v[100:101], v[166:167] op_sel_hi:[1,0]
	v_pk_mul_f32 v[102:103], v[102:103], v[166:167] op_sel_hi:[1,0]
	v_pk_mul_f32 v[104:105], v[104:105], v[166:167] op_sel_hi:[1,0]
	v_pk_mul_f32 v[106:107], v[106:107], v[166:167] op_sel_hi:[1,0]
	v_pk_mul_f32 v[108:109], v[108:109], v[166:167] op_sel_hi:[1,0]
	v_pk_mul_f32 v[110:111], v[110:111], v[166:167] op_sel_hi:[1,0]
	v_pk_mul_f32 v[114:115], v[114:115], v[166:167] op_sel_hi:[1,0]
	v_pk_mul_f32 v[116:117], v[116:117], v[166:167] op_sel_hi:[1,0]
	v_pk_mul_f32 v[118:119], v[118:119], v[166:167] op_sel_hi:[1,0]
	v_pk_mul_f32 v[120:121], v[120:121], v[166:167] op_sel_hi:[1,0]
	v_pk_mul_f32 v[122:123], v[122:123], v[166:167] op_sel_hi:[1,0]
	v_pk_mul_f32 v[124:125], v[124:125], v[166:167] op_sel_hi:[1,0]
	v_pk_mul_f32 v[126:127], v[126:127], v[166:167] op_sel_hi:[1,0]
	v_pk_mul_f32 v[128:129], v[128:129], v[166:167] op_sel_hi:[1,0]
	v_pk_fma_f32 v[130:131], v[0:1], v[96:97], v[130:131]
	v_pk_fma_f32 v[132:133], v[2:3], v[98:99], v[132:133]
	v_pk_fma_f32 v[134:135], v[4:5], v[100:101], v[134:135]
	v_pk_fma_f32 v[136:137], v[6:7], v[102:103], v[136:137]
	v_pk_fma_f32 v[138:139], v[8:9], v[104:105], v[138:139]
	v_pk_fma_f32 v[140:141], v[10:11], v[106:107], v[140:141]
	v_pk_fma_f32 v[142:143], v[12:13], v[108:109], v[142:143]
	v_pk_fma_f32 v[144:145], v[14:15], v[110:111], v[144:145]
	v_pk_fma_f32 v[146:147], v[16:17], v[114:115], v[146:147]
	v_pk_fma_f32 v[148:149], v[18:19], v[116:117], v[148:149]
	v_pk_fma_f32 v[150:151], v[20:21], v[118:119], v[150:151]
	v_pk_fma_f32 v[152:153], v[22:23], v[120:121], v[152:153]
	v_pk_fma_f32 v[154:155], v[24:25], v[122:123], v[154:155]
	v_pk_fma_f32 v[156:157], v[26:27], v[124:125], v[156:157]
	v_pk_fma_f32 v[158:159], v[28:29], v[126:127], v[158:159]
	v_pk_fma_f32 v[160:161], v[30:31], v[128:129], v[160:161]
	s_bitcmp1_b32 s11, 0
	s_cbranch_scc0 .Lrp_a_bf16
	s_add_u32 s12, s4, 0xfffff000
	s_addc_u32 s13, s5, -1
	global_store_dwordx4 v163, v[130:133], s[12:13] offset:0
	global_store_dwordx4 v163, v[134:137], s[12:13] offset:16
	global_store_dwordx4 v163, v[138:141], s[12:13] offset:2048
	global_store_dwordx4 v163, v[142:145], s[12:13] offset:2064
	global_store_dwordx4 v163, v[146:149], s[4:5] offset:0
	global_store_dwordx4 v163, v[150:153], s[4:5] offset:16
	global_store_dwordx4 v163, v[154:157], s[4:5] offset:2048
	global_store_dwordx4 v163, v[158:161], s[4:5] offset:2064
	s_branch .Lrp_a_stored
.Lrp_a_bf16:
	v_cvt_pk_bf16_f32 v32, v130, v131
	v_cvt_pk_bf16_f32 v33, v132, v133
	v_cvt_pk_bf16_f32 v34, v134, v135
	v_cvt_pk_bf16_f32 v35, v136, v137
	v_cvt_pk_bf16_f32 v36, v138, v139
	v_cvt_pk_bf16_f32 v37, v140, v141
	v_cvt_pk_bf16_f32 v38, v142, v143
	v_cvt_pk_bf16_f32 v39, v144, v145
	v_cvt_pk_bf16_f32 v40, v146, v147
	v_cvt_pk_bf16_f32 v41, v148, v149
	v_cvt_pk_bf16_f32 v42, v150, v151
	v_cvt_pk_bf16_f32 v43, v152, v153
	v_cvt_pk_bf16_f32 v44, v154, v155
	v_cvt_pk_bf16_f32 v45, v156, v157
	v_cvt_pk_bf16_f32 v46, v158, v159
	v_cvt_pk_bf16_f32 v47, v160, v161
	global_store_dwordx4 v162, v[32:35], s[4:5] offset:0
	global_store_dwordx4 v162, v[36:39], s[4:5] offset:1024
	global_store_dwordx4 v162, v[40:43], s[4:5] offset:2048
	global_store_dwordx4 v162, v[44:47], s[4:5] offset:3072
.Lrp_a_stored:
	s_bitcmp1_b32 s11, 1
	s_cbranch_scc0 .Lrp_a_norstd
	v_mul_f32_e32 v168, v130, v130
	v_mul_f32_e32 v169, v131, v131
	v_mul_f32_e32 v170, v132, v132
	v_mul_f32_e32 v171, v133, v133
	v_fmac_f32_e32 v168, v134, v134
	v_fmac_f32_e32 v169, v135, v135
	v_fmac_f32_e32 v170, v136, v136
	v_fmac_f32_e32 v171, v137, v137
	v_fmac_f32_e32 v168, v138, v138
	v_fmac_f32_e32 v169, v139, v139
	v_fmac_f32_e32 v170, v140, v140
	v_fmac_f32_e32 v171, v141, v141
	v_fmac_f32_e32 v168, v142, v142
	v_fmac_f32_e32 v169, v143, v143
	v_fmac_f32_e32 v170, v144, v144
	v_fmac_f32_e32 v171, v145, v145
	v_fmac_f32_e32 v168, v146, v146
	v_fmac_f32_e32 v169, v147, v147
	v_fmac_f32_e32 v170, v148, v148
	v_fmac_f32_e32 v171, v149, v149
	v_fmac_f32_e32 v168, v150, v150
	v_fmac_f32_e32 v169, v151, v151
	v_fmac_f32_e32 v170, v152, v152
	v_fmac_f32_e32 v171, v153, v153
	v_fmac_f32_e32 v168, v154, v154
	v_fmac_f32_e32 v169, v155, v155
	v_fmac_f32_e32 v170, v156, v156
	v_fmac_f32_e32 v171, v157, v157
	v_fmac_f32_e32 v168, v158, v158
	v_fmac_f32_e32 v169, v159, v159
	v_fmac_f32_e32 v170, v160, v160
	v_fmac_f32_e32 v171, v161, v161
	v_add_f32_e32 v168, v168, v169
	v_add_f32_e32 v170, v170, v171
	v_add_f32_e32 v164, v168, v170
	ds_swizzle_b32 v165, v164 offset:swizzle(SWAP,1)
	s_waitcnt lgkmcnt(0)
	v_add_f32_e32 v164, v164, v165
	ds_swizzle_b32 v165, v164 offset:swizzle(SWAP,2)
	s_waitcnt lgkmcnt(0)
	v_add_f32_e32 v164, v164, v165
	ds_swizzle_b32 v165, v164 offset:swizzle(SWAP,4)
	s_waitcnt lgkmcnt(0)
	v_add_f32_e32 v164, v164, v165
	ds_swizzle_b32 v165, v164 offset:swizzle(SWAP,8)
	s_waitcnt lgkmcnt(0)
	v_add_f32_e32 v164, v164, v165
	ds_swizzle_b32 v165, v164 offset:swizzle(SWAP,16)
	s_waitcnt lgkmcnt(0)
	v_add_f32_e32 v164, v164, v165
	v_mov_b32_e32 v165, v164
	s_nop 1
	v_permlane32_swap_b32_e32 v164, v165
	v_add_f32_e32 v164, v164, v165
	v_fmamk_f32 v167, v164, 0x3a000000, v180
	v_rsq_f32_e32 v167, v167
	s_nop 0
	s_mov_b64 exec, 1
	global_store_dword v113, v167, s[8:9]
	s_mov_b64 exec, -1
; DI float bflo(unsigned w) { return __uint_as_float(w << 16); }
; DI float bfhi(unsigned w) { return __uint_as_float(w & 0xffff0000u); }
; template <bool XINB, bool XOUTB> DI void row_resid_norm(const bf16* trow, const bf16* trow2, int npart, const void* xin, void* xout, const float* gpost, float* rstd_out, int lane) {
;     ...
; #pragma unroll
;   for (int j = 0; j < 8; ++j) {
;     if (npart == 8) { f32x4 acc4 = {0.f, 0.f, 0.f, 0.f};
; #pragma unroll
;       for (int p = 0; p < 8; ++p) { const u32x2 w = (tr2 + (size_t)p * (1024 * 2048 / 4))[64 * j]; acc4 += (f32x4){bflo(w.x), bfhi(w.x), bflo(w.y), bfhi(w.y)}; }
;       t[j] = acc4;
;     } else { const u32x2 w = tr[64 * j]; u32x2 w2 = {0u, 0u}; if (npart == 1) w2 = tr2[64 * j]; t[j] = (f32x4){bflo(w.x) + bflo(w2.x), bfhi(w.x) + bfhi(w2.x), bflo(w.y) + bflo(w2.y), bfhi(w.y) + bfhi(w2.y)}; }
;     s += (t[j].x * t[j].x + t[j].y * t[j].y) + (t[j].z * t[j].z + t[j].w * t[j].w); }
; #pragma unroll
;   for (int j = 0; j < 8; ++j) { if (XINB) { const u32x2 w = ((const u32x2*)xin + lane)[64 * j]; x[j] = (f32x4){bflo(w.x), bfhi(w.x), bflo(w.y), bfhi(w.y)}; } else x[j] = ((const f32x4*)xin + lane)[64 * j]; }
.Lrp_a_norstd:
	s_nop 1
	s_add_u32 s4, s4, 0x1000000
	s_addc_u32 s5, s5, 0
	s_add_u32 s8, s8, 0x2000
	s_addc_u32 s9, s9, 0
	s_add_i32 s6, s6, 1
	s_cmp_lt_u32 s6, 8
	s_cbranch_scc1 .Lrp_loop
	s_cmpk_lt_i32 s72, 0x400
	s_cbranch_scc0 .Lrp_done
	s_lshl_b32 s0, s72, 12
	s_add_u32 s0, s0, s10
	s_add_u32 s0, s54, s0
	s_addc_u32 s1, s55, 0
	global_load_dwordx4 v[48:51], v162, s[4:5] offset:0
	global_load_dwordx4 v[52:55], v162, s[4:5] offset:1024
	global_load_dwordx4 v[56:59], v162, s[4:5] offset:2048
	global_load_dwordx4 v[60:63], v162, s[4:5] offset:3072
	global_load_dwordx4 v[64:67], v162, s[0:1] offset:0
	global_load_dwordx4 v[68:71], v162, s[0:1] offset:1024
	global_load_dwordx4 v[72:75], v162, s[0:1] offset:2048
	global_load_dwordx4 v[76:79], v162, s[0:1] offset:3072
	s_add_u32 s0, s0, 0x400000
	s_addc_u32 s1, s1, 0
	global_load_dwordx4 v[80:83], v162, s[0:1] offset:0
	global_load_dwordx4 v[84:87], v162, s[0:1] offset:1024
	global_load_dwordx4 v[88:91], v162, s[0:1] offset:2048
	global_load_dwordx4 v[92:95], v162, s[0:1] offset:3072
	s_add_u32 s0, s0, 0x400000
	s_addc_u32 s1, s1, 0
	global_load_dwordx4 v[130:133], v162, s[0:1] offset:0
	global_load_dwordx4 v[134:137], v162, s[0:1] offset:1024
	global_load_dwordx4 v[138:141], v162, s[0:1] offset:2048
	global_load_dwordx4 v[142:145], v162, s[0:1] offset:3072
	s_add_u32 s0, s0, 0x400000
	s_addc_u32 s1, s1, 0
	global_load_dwordx4 v[146:149], v162, s[0:1] offset:0
	global_load_dwordx4 v[150:153], v162, s[0:1] offset:1024
	global_load_dwordx4 v[154:157], v162, s[0:1] offset:2048
	global_load_dwordx4 v[158:161], v162, s[0:1] offset:3072
	s_add_u32 s0, s0, 0x400000
	s_addc_u32 s1, s1, 0
	s_waitcnt vmcnt(0)
	v_lshlrev_b32_e32 v96, 16, v64
	v_and_b32_e32 v97, 0xffff0000, v64
	v_lshlrev_b32_e32 v98, 16, v65
	v_and_b32_e32 v99, 0xffff0000, v65
	v_lshlrev_b32_e32 v100, 16, v66
	v_and_b32_e32 v101, 0xffff0000, v66
	v_lshlrev_b32_e32 v102, 16, v67
	v_and_b32_e32 v103, 0xffff0000, v67
	v_lshlrev_b32_e32 v104, 16, v68
	v_and_b32_e32 v105, 0xffff0000, v68
	v_lshlrev_b32_e32 v106, 16, v69
	v_and_b32_e32 v107, 0xffff0000, v69
	v_lshlrev_b32_e32 v108, 16, v70
	v_and_b32_e32 v109, 0xffff0000, v70
	v_lshlrev_b32_e32 v110, 16, v71
	v_and_b32_e32 v111, 0xffff0000, v71
	v_lshlrev_b32_e32 v114, 16, v72
	v_and_b32_e32 v115, 0xffff0000, v72
	v_lshlrev_b32_e32 v116, 16, v73
	v_and_b32_e32 v117, 0xffff0000, v73
	v_lshlrev_b32_e32 v118, 16, v74
	v_and_b32_e32 v119, 0xffff0000, v74
	v_lshlrev_b32_e32 v120, 16, v75
	v_and_b32_e32 v121, 0xffff0000, v75
	v_lshlrev_b32_e32 v122, 16, v76
	v_and_b32_e32 v123, 0xffff0000, v76
	v_lshlrev_b32_e32 v124, 16, v77
	v_and_b32_e32 v125, 0xffff0000, v77
	v_lshlrev_b32_e32 v126, 16, v78
	v_and_b32_e32 v127, 0xffff0000, v78
	v_lshlrev_b32_e32 v128, 16, v79
	v_and_b32_e32 v129, 0xffff0000, v79
	v_lshlrev_b32_e32 v168, 16, v80
	v_and_b32_e32 v169, 0xffff0000, v80
	v_add_f32_e32 v96, v96, v168
	v_add_f32_e32 v97, v97, v169
	v_lshlrev_b32_e32 v168, 16, v81
	v_and_b32_e32 v169, 0xffff0000, v81
	v_add_f32_e32 v98, v98, v168
	v_add_f32_e32 v99, v99, v169
	v_lshlrev_b32_e32 v168, 16, v82
	v_and_b32_e32 v169, 0xffff0000, v82
	v_add_f32_e32 v100, v100, v168
	v_add_f32_e32 v101, v101, v169
	v_lshlrev_b32_e32 v168, 16, v83
	v_and_b32_e32 v169, 0xffff0000, v83
	v_add_f32_e32 v102, v102, v168
	v_add_f32_e32 v103, v103, v169
	v_lshlrev_b32_e32 v168, 16, v84
	v_and_b32_e32 v169, 0xffff0000, v84
	v_add_f32_e32 v104, v104, v168
	v_add_f32_e32 v105, v105, v169
	v_lshlrev_b32_e32 v168, 16, v85
	v_and_b32_e32 v169, 0xffff0000, v85
	v_add_f32_e32 v106, v106, v168
	v_add_f32_e32 v107, v107, v169
	v_lshlrev_b32_e32 v168, 16, v86
	v_and_b32_e32 v169, 0xffff0000, v86
	v_add_f32_e32 v108, v108, v168
	v_add_f32_e32 v109, v109, v169
	v_lshlrev_b32_e32 v168, 16, v87
	v_and_b32_e32 v169, 0xffff0000, v87
	v_add_f32_e32 v110, v110, v168
	v_add_f32_e32 v111, v111, v169
	v_lshlrev_b32_e32 v168, 16, v88
	v_and_b32_e32 v169, 0xffff0000, v88
	v_add_f32_e32 v114, v114, v168
	v_add_f32_e32 v115, v115, v169
	v_lshlrev_b32_e32 v168, 16, v89
	v_and_b32_e32 v169, 0xffff0000, v89
	v_add_f32_e32 v116, v116, v168
	v_add_f32_e32 v117, v117, v169
	v_lshlrev_b32_e32 v168, 16, v90
	v_and_b32_e32 v169, 0xffff0000, v90
	v_add_f32_e32 v118, v118, v168
	v_add_f32_e32 v119, v119, v169
	v_lshlrev_b32_e32 v168, 16, v91
	v_and_b32_e32 v169, 0xffff0000, v91
	v_add_f32_e32 v120, v120, v168
	v_add_f32_e32 v121, v121, v169
	v_lshlrev_b32_e32 v168, 16, v92
	v_and_b32_e32 v169, 0xffff0000, v92
	v_add_f32_e32 v122, v122, v168
	v_add_f32_e32 v123, v123, v169
	v_lshlrev_b32_e32 v168, 16, v93
	v_and_b32_e32 v169, 0xffff0000, v93
	v_add_f32_e32 v124, v124, v168
	v_add_f32_e32 v125, v125, v169
	v_lshlrev_b32_e32 v168, 16, v94
	v_and_b32_e32 v169, 0xffff0000, v94
	v_add_f32_e32 v126, v126, v168
	v_add_f32_e32 v127, v127, v169
	v_lshlrev_b32_e32 v168, 16, v95
	v_and_b32_e32 v169, 0xffff0000, v95
	v_add_f32_e32 v128, v128, v168
	v_add_f32_e32 v129, v129, v169
	v_lshlrev_b32_e32 v168, 16, v130
	v_and_b32_e32 v169, 0xffff0000, v130
	v_add_f32_e32 v96, v96, v168
	v_add_f32_e32 v97, v97, v169
	v_lshlrev_b32_e32 v168, 16, v131
	v_and_b32_e32 v169, 0xffff0000, v131
	v_add_f32_e32 v98, v98, v168
	v_add_f32_e32 v99, v99, v169
	v_lshlrev_b32_e32 v168, 16, v132
	v_and_b32_e32 v169, 0xffff0000, v132
	v_add_f32_e32 v100, v100, v168
	v_add_f32_e32 v101, v101, v169
	v_lshlrev_b32_e32 v168, 16, v133
	v_and_b32_e32 v169, 0xffff0000, v133
	v_add_f32_e32 v102, v102, v168
	v_add_f32_e32 v103, v103, v169
	v_lshlrev_b32_e32 v168, 16, v134
	v_and_b32_e32 v169, 0xffff0000, v134
	v_add_f32_e32 v104, v104, v168
	v_add_f32_e32 v105, v105, v169
	v_lshlrev_b32_e32 v168, 16, v135
; DI float bflo(unsigned w) { return __uint_as_float(w << 16); }
; DI float bfhi(unsigned w) { return __uint_as_float(w & 0xffff0000u); }
; template <bool XINB, bool XOUTB> DI void row_resid_norm(const bf16* trow, const bf16* trow2, int npart, const void* xin, void* xout, const float* gpost, float* rstd_out, int lane) {
;     ...
;     if (npart == 8) { f32x4 acc4 = {0.f, 0.f, 0.f, 0.f};
; #pragma unroll
;       for (int p = 0; p < 8; ++p) { const u32x2 w = (tr2 + (size_t)p * (1024 * 2048 / 4))[64 * j]; acc4 += (f32x4){bflo(w.x), bfhi(w.x), bflo(w.y), bfhi(w.y)}; }
;       t[j] = acc4;
	v_and_b32_e32 v169, 0xffff0000, v135
	v_add_f32_e32 v106, v106, v168
	v_add_f32_e32 v107, v107, v169
	v_lshlrev_b32_e32 v168, 16, v136
	v_and_b32_e32 v169, 0xffff0000, v136
	v_add_f32_e32 v108, v108, v168
	v_add_f32_e32 v109, v109, v169
	v_lshlrev_b32_e32 v168, 16, v137
	v_and_b32_e32 v169, 0xffff0000, v137
	v_add_f32_e32 v110, v110, v168
	v_add_f32_e32 v111, v111, v169
	v_lshlrev_b32_e32 v168, 16, v138
	v_and_b32_e32 v169, 0xffff0000, v138
	v_add_f32_e32 v114, v114, v168
	v_add_f32_e32 v115, v115, v169
	v_lshlrev_b32_e32 v168, 16, v139
	v_and_b32_e32 v169, 0xffff0000, v139
	v_add_f32_e32 v116, v116, v168
	v_add_f32_e32 v117, v117, v169
	v_lshlrev_b32_e32 v168, 16, v140
	v_and_b32_e32 v169, 0xffff0000, v140
	v_add_f32_e32 v118, v118, v168
	v_add_f32_e32 v119, v119, v169
	v_lshlrev_b32_e32 v168, 16, v141
	v_and_b32_e32 v169, 0xffff0000, v141
	v_add_f32_e32 v120, v120, v168
	v_add_f32_e32 v121, v121, v169
	v_lshlrev_b32_e32 v168, 16, v142
	v_and_b32_e32 v169, 0xffff0000, v142
	v_add_f32_e32 v122, v122, v168
	v_add_f32_e32 v123, v123, v169
	v_lshlrev_b32_e32 v168, 16, v143
	v_and_b32_e32 v169, 0xffff0000, v143
	v_add_f32_e32 v124, v124, v168
	v_add_f32_e32 v125, v125, v169
	v_lshlrev_b32_e32 v168, 16, v144
	v_and_b32_e32 v169, 0xffff0000, v144
	v_add_f32_e32 v126, v126, v168
	v_add_f32_e32 v127, v127, v169
	v_lshlrev_b32_e32 v168, 16, v145
	v_and_b32_e32 v169, 0xffff0000, v145
	v_add_f32_e32 v128, v128, v168
	v_add_f32_e32 v129, v129, v169
	v_lshlrev_b32_e32 v168, 16, v146
	v_and_b32_e32 v169, 0xffff0000, v146
	v_add_f32_e32 v96, v96, v168
	v_add_f32_e32 v97, v97, v169
	v_lshlrev_b32_e32 v168, 16, v147
	v_and_b32_e32 v169, 0xffff0000, v147
	v_add_f32_e32 v98, v98, v168
	v_add_f32_e32 v99, v99, v169
	v_lshlrev_b32_e32 v168, 16, v148
	v_and_b32_e32 v169, 0xffff0000, v148
	v_add_f32_e32 v100, v100, v168
	v_add_f32_e32 v101, v101, v169
	v_lshlrev_b32_e32 v168, 16, v149
	v_and_b32_e32 v169, 0xffff0000, v149
	v_add_f32_e32 v102, v102, v168
	v_add_f32_e32 v103, v103, v169
	v_lshlrev_b32_e32 v168, 16, v150
	v_and_b32_e32 v169, 0xffff0000, v150
	v_add_f32_e32 v104, v104, v168
	v_add_f32_e32 v105, v105, v169
	v_lshlrev_b32_e32 v168, 16, v151
	v_and_b32_e32 v169, 0xffff0000, v151
	v_add_f32_e32 v106, v106, v168
	v_add_f32_e32 v107, v107, v169
	v_lshlrev_b32_e32 v168, 16, v152
	v_and_b32_e32 v169, 0xffff0000, v152
	v_add_f32_e32 v108, v108, v168
	v_add_f32_e32 v109, v109, v169
	v_lshlrev_b32_e32 v168, 16, v153
	v_and_b32_e32 v169, 0xffff0000, v153
	v_add_f32_e32 v110, v110, v168
	v_add_f32_e32 v111, v111, v169
	v_lshlrev_b32_e32 v168, 16, v154
	v_and_b32_e32 v169, 0xffff0000, v154
	v_add_f32_e32 v114, v114, v168
	v_add_f32_e32 v115, v115, v169
	v_lshlrev_b32_e32 v168, 16, v155
	v_and_b32_e32 v169, 0xffff0000, v155
	v_add_f32_e32 v116, v116, v168
	v_add_f32_e32 v117, v117, v169
	v_lshlrev_b32_e32 v168, 16, v156
	v_and_b32_e32 v169, 0xffff0000, v156
	v_add_f32_e32 v118, v118, v168
	v_add_f32_e32 v119, v119, v169
	v_lshlrev_b32_e32 v168, 16, v157
	v_and_b32_e32 v169, 0xffff0000, v157
	v_add_f32_e32 v120, v120, v168
	v_add_f32_e32 v121, v121, v169
	v_lshlrev_b32_e32 v168, 16, v158
	v_and_b32_e32 v169, 0xffff0000, v158
	v_add_f32_e32 v122, v122, v168
	v_add_f32_e32 v123, v123, v169
	v_lshlrev_b32_e32 v168, 16, v159
	v_and_b32_e32 v169, 0xffff0000, v159
	v_add_f32_e32 v124, v124, v168
	v_add_f32_e32 v125, v125, v169
	v_lshlrev_b32_e32 v168, 16, v160
	v_and_b32_e32 v169, 0xffff0000, v160
	v_add_f32_e32 v126, v126, v168
	v_add_f32_e32 v127, v127, v169
	v_lshlrev_b32_e32 v168, 16, v161
	v_and_b32_e32 v169, 0xffff0000, v161
	v_add_f32_e32 v128, v128, v168
	v_add_f32_e32 v129, v129, v169
	global_load_dwordx4 v[64:67], v162, s[0:1] offset:0
	global_load_dwordx4 v[68:71], v162, s[0:1] offset:1024
	global_load_dwordx4 v[72:75], v162, s[0:1] offset:2048
	global_load_dwordx4 v[76:79], v162, s[0:1] offset:3072
	s_add_u32 s0, s0, 0x400000
	s_addc_u32 s1, s1, 0
	global_load_dwordx4 v[80:83], v162, s[0:1] offset:0
	global_load_dwordx4 v[84:87], v162, s[0:1] offset:1024
	global_load_dwordx4 v[88:91], v162, s[0:1] offset:2048
	global_load_dwordx4 v[92:95], v162, s[0:1] offset:3072
	s_add_u32 s0, s0, 0x400000
	s_addc_u32 s1, s1, 0
	global_load_dwordx4 v[130:133], v162, s[0:1] offset:0
	global_load_dwordx4 v[134:137], v162, s[0:1] offset:1024
	global_load_dwordx4 v[138:141], v162, s[0:1] offset:2048
	global_load_dwordx4 v[142:145], v162, s[0:1] offset:3072
	s_add_u32 s0, s0, 0x400000
	s_addc_u32 s1, s1, 0
	global_load_dwordx4 v[146:149], v162, s[0:1] offset:0
	global_load_dwordx4 v[150:153], v162, s[0:1] offset:1024
	global_load_dwordx4 v[154:157], v162, s[0:1] offset:2048
	global_load_dwordx4 v[158:161], v162, s[0:1] offset:3072
	s_add_u32 s0, s0, 0x400000
	s_addc_u32 s1, s1, 0
	s_waitcnt vmcnt(0)
; DI float bflo(unsigned w) { return __uint_as_float(w << 16); }
; DI float bfhi(unsigned w) { return __uint_as_float(w & 0xffff0000u); }
; template <bool XINB, bool XOUTB> DI void row_resid_norm(const bf16* trow, const bf16* trow2, int npart, const void* xin, void* xout, const float* gpost, float* rstd_out, int lane) {
;     ...
;     if (npart == 8) { f32x4 acc4 = {0.f, 0.f, 0.f, 0.f};
; #pragma unroll
;       for (int p = 0; p < 8; ++p) { const u32x2 w = (tr2 + (size_t)p * (1024 * 2048 / 4))[64 * j]; acc4 += (f32x4){bflo(w.x), bfhi(w.x), bflo(w.y), bfhi(w.y)}; }
;       t[j] = acc4;
	v_lshlrev_b32_e32 v168, 16, v64
	v_and_b32_e32 v169, 0xffff0000, v64
	v_add_f32_e32 v96, v96, v168
	v_add_f32_e32 v97, v97, v169
	v_lshlrev_b32_e32 v168, 16, v65
	v_and_b32_e32 v169, 0xffff0000, v65
	v_add_f32_e32 v98, v98, v168
	v_add_f32_e32 v99, v99, v169
	v_lshlrev_b32_e32 v168, 16, v66
	v_and_b32_e32 v169, 0xffff0000, v66
	v_add_f32_e32 v100, v100, v168
	v_add_f32_e32 v101, v101, v169
	v_lshlrev_b32_e32 v168, 16, v67
	v_and_b32_e32 v169, 0xffff0000, v67
	v_add_f32_e32 v102, v102, v168
	v_add_f32_e32 v103, v103, v169
	v_lshlrev_b32_e32 v168, 16, v68
	v_and_b32_e32 v169, 0xffff0000, v68
	v_add_f32_e32 v104, v104, v168
	v_add_f32_e32 v105, v105, v169
	v_lshlrev_b32_e32 v168, 16, v69
	v_and_b32_e32 v169, 0xffff0000, v69
	v_add_f32_e32 v106, v106, v168
	v_add_f32_e32 v107, v107, v169
	v_lshlrev_b32_e32 v168, 16, v70
	v_and_b32_e32 v169, 0xffff0000, v70
	v_add_f32_e32 v108, v108, v168
	v_add_f32_e32 v109, v109, v169
	v_lshlrev_b32_e32 v168, 16, v71
	v_and_b32_e32 v169, 0xffff0000, v71
	v_add_f32_e32 v110, v110, v168
	v_add_f32_e32 v111, v111, v169
	v_lshlrev_b32_e32 v168, 16, v72
	v_and_b32_e32 v169, 0xffff0000, v72
	v_add_f32_e32 v114, v114, v168
	v_add_f32_e32 v115, v115, v169
	v_lshlrev_b32_e32 v168, 16, v73
	v_and_b32_e32 v169, 0xffff0000, v73
	v_add_f32_e32 v116, v116, v168
	v_add_f32_e32 v117, v117, v169
	v_lshlrev_b32_e32 v168, 16, v74
	v_and_b32_e32 v169, 0xffff0000, v74
	v_add_f32_e32 v118, v118, v168
	v_add_f32_e32 v119, v119, v169
	v_lshlrev_b32_e32 v168, 16, v75
	v_and_b32_e32 v169, 0xffff0000, v75
	v_add_f32_e32 v120, v120, v168
	v_add_f32_e32 v121, v121, v169
	v_lshlrev_b32_e32 v168, 16, v76
	v_and_b32_e32 v169, 0xffff0000, v76
	v_add_f32_e32 v122, v122, v168
	v_add_f32_e32 v123, v123, v169
	v_lshlrev_b32_e32 v168, 16, v77
	v_and_b32_e32 v169, 0xffff0000, v77
	v_add_f32_e32 v124, v124, v168
	v_add_f32_e32 v125, v125, v169
	v_lshlrev_b32_e32 v168, 16, v78
	v_and_b32_e32 v169, 0xffff0000, v78
	v_add_f32_e32 v126, v126, v168
	v_add_f32_e32 v127, v127, v169
	v_lshlrev_b32_e32 v168, 16, v79
	v_and_b32_e32 v169, 0xffff0000, v79
	v_add_f32_e32 v128, v128, v168
	v_add_f32_e32 v129, v129, v169
	v_lshlrev_b32_e32 v168, 16, v80
	v_and_b32_e32 v169, 0xffff0000, v80
	v_add_f32_e32 v96, v96, v168
	v_add_f32_e32 v97, v97, v169
	v_lshlrev_b32_e32 v168, 16, v81
	v_and_b32_e32 v169, 0xffff0000, v81
	v_add_f32_e32 v98, v98, v168
	v_add_f32_e32 v99, v99, v169
	v_lshlrev_b32_e32 v168, 16, v82
	v_and_b32_e32 v169, 0xffff0000, v82
	v_add_f32_e32 v100, v100, v168
	v_add_f32_e32 v101, v101, v169
	v_lshlrev_b32_e32 v168, 16, v83
	v_and_b32_e32 v169, 0xffff0000, v83
	v_add_f32_e32 v102, v102, v168
	v_add_f32_e32 v103, v103, v169
	v_lshlrev_b32_e32 v168, 16, v84
	v_and_b32_e32 v169, 0xffff0000, v84
	v_add_f32_e32 v104, v104, v168
	v_add_f32_e32 v105, v105, v169
	v_lshlrev_b32_e32 v168, 16, v85
	v_and_b32_e32 v169, 0xffff0000, v85
	v_add_f32_e32 v106, v106, v168
	v_add_f32_e32 v107, v107, v169
	v_lshlrev_b32_e32 v168, 16, v86
	v_and_b32_e32 v169, 0xffff0000, v86
	v_add_f32_e32 v108, v108, v168
	v_add_f32_e32 v109, v109, v169
	v_lshlrev_b32_e32 v168, 16, v87
	v_and_b32_e32 v169, 0xffff0000, v87
	v_add_f32_e32 v110, v110, v168
	v_add_f32_e32 v111, v111, v169
	v_lshlrev_b32_e32 v168, 16, v88
	v_and_b32_e32 v169, 0xffff0000, v88
	v_add_f32_e32 v114, v114, v168
	v_add_f32_e32 v115, v115, v169
	v_lshlrev_b32_e32 v168, 16, v89
	v_and_b32_e32 v169, 0xffff0000, v89
	v_add_f32_e32 v116, v116, v168
	v_add_f32_e32 v117, v117, v169
	v_lshlrev_b32_e32 v168, 16, v90
	v_and_b32_e32 v169, 0xffff0000, v90
	v_add_f32_e32 v118, v118, v168
	v_add_f32_e32 v119, v119, v169
	v_lshlrev_b32_e32 v168, 16, v91
	v_and_b32_e32 v169, 0xffff0000, v91
	v_add_f32_e32 v120, v120, v168
	v_add_f32_e32 v121, v121, v169
	v_lshlrev_b32_e32 v168, 16, v92
	v_and_b32_e32 v169, 0xffff0000, v92
	v_add_f32_e32 v122, v122, v168
	v_add_f32_e32 v123, v123, v169
	v_lshlrev_b32_e32 v168, 16, v93
	v_and_b32_e32 v169, 0xffff0000, v93
	v_add_f32_e32 v124, v124, v168
	v_add_f32_e32 v125, v125, v169
	v_lshlrev_b32_e32 v168, 16, v94
	v_and_b32_e32 v169, 0xffff0000, v94
	v_add_f32_e32 v126, v126, v168
	v_add_f32_e32 v127, v127, v169
	v_lshlrev_b32_e32 v168, 16, v95
	v_and_b32_e32 v169, 0xffff0000, v95
	v_add_f32_e32 v128, v128, v168
	v_add_f32_e32 v129, v129, v169
	v_lshlrev_b32_e32 v168, 16, v130
	v_and_b32_e32 v169, 0xffff0000, v130
	v_add_f32_e32 v96, v96, v168
	v_add_f32_e32 v97, v97, v169
	v_lshlrev_b32_e32 v168, 16, v131
	v_and_b32_e32 v169, 0xffff0000, v131
	v_add_f32_e32 v98, v98, v168
	v_add_f32_e32 v99, v99, v169
	v_lshlrev_b32_e32 v168, 16, v132
	v_and_b32_e32 v169, 0xffff0000, v132
	v_add_f32_e32 v100, v100, v168
	v_add_f32_e32 v101, v101, v169
	v_lshlrev_b32_e32 v168, 16, v133
	v_and_b32_e32 v169, 0xffff0000, v133
	v_add_f32_e32 v102, v102, v168
	v_add_f32_e32 v103, v103, v169
	v_lshlrev_b32_e32 v168, 16, v134
	v_and_b32_e32 v169, 0xffff0000, v134
	v_add_f32_e32 v104, v104, v168
	v_add_f32_e32 v105, v105, v169
	v_lshlrev_b32_e32 v168, 16, v135
	v_and_b32_e32 v169, 0xffff0000, v135
	v_add_f32_e32 v106, v106, v168
	v_add_f32_e32 v107, v107, v169
	v_lshlrev_b32_e32 v168, 16, v136
	v_and_b32_e32 v169, 0xffff0000, v136
	v_add_f32_e32 v108, v108, v168
	v_add_f32_e32 v109, v109, v169
	v_lshlrev_b32_e32 v168, 16, v137
	v_and_b32_e32 v169, 0xffff0000, v137
	v_add_f32_e32 v110, v110, v168
	v_add_f32_e32 v111, v111, v169
	v_lshlrev_b32_e32 v168, 16, v138
	v_and_b32_e32 v169, 0xffff0000, v138
	v_add_f32_e32 v114, v114, v168
	v_add_f32_e32 v115, v115, v169
	v_lshlrev_b32_e32 v168, 16, v139
	v_and_b32_e32 v169, 0xffff0000, v139
	v_add_f32_e32 v116, v116, v168
	v_add_f32_e32 v117, v117, v169
; DI float bflo(unsigned w) { return __uint_as_float(w << 16); }
; DI float bfhi(unsigned w) { return __uint_as_float(w & 0xffff0000u); }
; template <bool XINB, bool XOUTB> DI void row_resid_norm(const bf16* trow, const bf16* trow2, int npart, const void* xin, void* xout, const float* gpost, float* rstd_out, int lane) {
;     ...
;     if (npart == 8) { f32x4 acc4 = {0.f, 0.f, 0.f, 0.f};
; #pragma unroll
;       for (int p = 0; p < 8; ++p) { const u32x2 w = (tr2 + (size_t)p * (1024 * 2048 / 4))[64 * j]; acc4 += (f32x4){bflo(w.x), bfhi(w.x), bflo(w.y), bfhi(w.y)}; }
;       t[j] = acc4;
;     } else { const u32x2 w = tr[64 * j]; u32x2 w2 = {0u, 0u}; if (npart == 1) w2 = tr2[64 * j]; t[j] = (f32x4){bflo(w.x) + bflo(w2.x), bfhi(w.x) + bfhi(w2.x), bflo(w.y) + bflo(w2.y), bfhi(w.y) + bfhi(w2.y)}; }
;     s += (t[j].x * t[j].x + t[j].y * t[j].y) + (t[j].z * t[j].z + t[j].w * t[j].w); }
; #pragma unroll
;   for (int j = 0; j < 8; ++j) { if (XINB) { const u32x2 w = ((const u32x2*)xin + lane)[64 * j]; x[j] = (f32x4){bflo(w.x), bfhi(w.x), bflo(w.y), bfhi(w.y)}; } else x[j] = ((const f32x4*)xin + lane)[64 * j]; }
;   const float rstd = rsqrtf(wave_sum(s) * (1.f / DM) + EPS);
	v_lshlrev_b32_e32 v168, 16, v140
	v_and_b32_e32 v169, 0xffff0000, v140
	v_add_f32_e32 v118, v118, v168
	v_add_f32_e32 v119, v119, v169
	v_lshlrev_b32_e32 v168, 16, v141
	v_and_b32_e32 v169, 0xffff0000, v141
	v_add_f32_e32 v120, v120, v168
	v_add_f32_e32 v121, v121, v169
	v_lshlrev_b32_e32 v168, 16, v142
	v_and_b32_e32 v169, 0xffff0000, v142
	v_add_f32_e32 v122, v122, v168
	v_add_f32_e32 v123, v123, v169
	v_lshlrev_b32_e32 v168, 16, v143
	v_and_b32_e32 v169, 0xffff0000, v143
	v_add_f32_e32 v124, v124, v168
	v_add_f32_e32 v125, v125, v169
	v_lshlrev_b32_e32 v168, 16, v144
	v_and_b32_e32 v169, 0xffff0000, v144
	v_add_f32_e32 v126, v126, v168
	v_add_f32_e32 v127, v127, v169
	v_lshlrev_b32_e32 v168, 16, v145
	v_and_b32_e32 v169, 0xffff0000, v145
	v_add_f32_e32 v128, v128, v168
	v_add_f32_e32 v129, v129, v169
	v_lshlrev_b32_e32 v168, 16, v146
	v_and_b32_e32 v169, 0xffff0000, v146
	v_add_f32_e32 v96, v96, v168
	v_add_f32_e32 v97, v97, v169
	v_lshlrev_b32_e32 v168, 16, v147
	v_and_b32_e32 v169, 0xffff0000, v147
	v_add_f32_e32 v98, v98, v168
	v_add_f32_e32 v99, v99, v169
	v_lshlrev_b32_e32 v168, 16, v148
	v_and_b32_e32 v169, 0xffff0000, v148
	v_add_f32_e32 v100, v100, v168
	v_add_f32_e32 v101, v101, v169
	v_lshlrev_b32_e32 v168, 16, v149
	v_and_b32_e32 v169, 0xffff0000, v149
	v_add_f32_e32 v102, v102, v168
	v_add_f32_e32 v103, v103, v169
	v_lshlrev_b32_e32 v168, 16, v150
	v_and_b32_e32 v169, 0xffff0000, v150
	v_add_f32_e32 v104, v104, v168
	v_add_f32_e32 v105, v105, v169
	v_lshlrev_b32_e32 v168, 16, v151
	v_and_b32_e32 v169, 0xffff0000, v151
	v_add_f32_e32 v106, v106, v168
	v_add_f32_e32 v107, v107, v169
	v_lshlrev_b32_e32 v168, 16, v152
	v_and_b32_e32 v169, 0xffff0000, v152
	v_add_f32_e32 v108, v108, v168
	v_add_f32_e32 v109, v109, v169
	v_lshlrev_b32_e32 v168, 16, v153
	v_and_b32_e32 v169, 0xffff0000, v153
	v_add_f32_e32 v110, v110, v168
	v_add_f32_e32 v111, v111, v169
	v_lshlrev_b32_e32 v168, 16, v154
	v_and_b32_e32 v169, 0xffff0000, v154
	v_add_f32_e32 v114, v114, v168
	v_add_f32_e32 v115, v115, v169
	v_lshlrev_b32_e32 v168, 16, v155
	v_and_b32_e32 v169, 0xffff0000, v155
	v_add_f32_e32 v116, v116, v168
	v_add_f32_e32 v117, v117, v169
	v_lshlrev_b32_e32 v168, 16, v156
	v_and_b32_e32 v169, 0xffff0000, v156
	v_add_f32_e32 v118, v118, v168
	v_add_f32_e32 v119, v119, v169
	v_lshlrev_b32_e32 v168, 16, v157
	v_and_b32_e32 v169, 0xffff0000, v157
	v_add_f32_e32 v120, v120, v168
	v_add_f32_e32 v121, v121, v169
	v_lshlrev_b32_e32 v168, 16, v158
	v_and_b32_e32 v169, 0xffff0000, v158
	v_add_f32_e32 v122, v122, v168
	v_add_f32_e32 v123, v123, v169
	v_lshlrev_b32_e32 v168, 16, v159
	v_and_b32_e32 v169, 0xffff0000, v159
	v_add_f32_e32 v124, v124, v168
	v_add_f32_e32 v125, v125, v169
	v_lshlrev_b32_e32 v168, 16, v160
	v_and_b32_e32 v169, 0xffff0000, v160
	v_add_f32_e32 v126, v126, v168
	v_add_f32_e32 v127, v127, v169
	v_lshlrev_b32_e32 v168, 16, v161
	v_and_b32_e32 v169, 0xffff0000, v161
	v_add_f32_e32 v128, v128, v168
	v_add_f32_e32 v129, v129, v169
	v_mul_f32_e32 v168, v96, v96
	v_mul_f32_e32 v169, v97, v97
	v_mul_f32_e32 v170, v98, v98
	v_mul_f32_e32 v171, v99, v99
	v_fmac_f32_e32 v168, v100, v100
	v_fmac_f32_e32 v169, v101, v101
	v_fmac_f32_e32 v170, v102, v102
	v_fmac_f32_e32 v171, v103, v103
	v_fmac_f32_e32 v168, v104, v104
	v_fmac_f32_e32 v169, v105, v105
	v_fmac_f32_e32 v170, v106, v106
	v_fmac_f32_e32 v171, v107, v107
	v_fmac_f32_e32 v168, v108, v108
	v_fmac_f32_e32 v169, v109, v109
	v_fmac_f32_e32 v170, v110, v110
	v_fmac_f32_e32 v171, v111, v111
	v_fmac_f32_e32 v168, v114, v114
	v_fmac_f32_e32 v169, v115, v115
	v_fmac_f32_e32 v170, v116, v116
	v_fmac_f32_e32 v171, v117, v117
	v_fmac_f32_e32 v168, v118, v118
	v_fmac_f32_e32 v169, v119, v119
	v_fmac_f32_e32 v170, v120, v120
	v_fmac_f32_e32 v171, v121, v121
	v_fmac_f32_e32 v168, v122, v122
	v_fmac_f32_e32 v169, v123, v123
	v_fmac_f32_e32 v170, v124, v124
	v_fmac_f32_e32 v171, v125, v125
	v_fmac_f32_e32 v168, v126, v126
	v_fmac_f32_e32 v169, v127, v127
	v_fmac_f32_e32 v170, v128, v128
	v_fmac_f32_e32 v171, v129, v129
	v_add_f32_e32 v168, v168, v169
	v_add_f32_e32 v170, v170, v171
	v_add_f32_e32 v164, v168, v170
	v_lshlrev_b32_e32 v130, 16, v48
	v_and_b32_e32 v131, 0xffff0000, v48
	v_lshlrev_b32_e32 v132, 16, v49
	v_and_b32_e32 v133, 0xffff0000, v49
	v_lshlrev_b32_e32 v134, 16, v50
	v_and_b32_e32 v135, 0xffff0000, v50
	v_lshlrev_b32_e32 v136, 16, v51
	v_and_b32_e32 v137, 0xffff0000, v51
	v_lshlrev_b32_e32 v138, 16, v52
	v_and_b32_e32 v139, 0xffff0000, v52
	v_lshlrev_b32_e32 v140, 16, v53
	v_and_b32_e32 v141, 0xffff0000, v53
	v_lshlrev_b32_e32 v142, 16, v54
	v_and_b32_e32 v143, 0xffff0000, v54
	v_lshlrev_b32_e32 v144, 16, v55
	v_and_b32_e32 v145, 0xffff0000, v55
	v_lshlrev_b32_e32 v146, 16, v56
	v_and_b32_e32 v147, 0xffff0000, v56
	v_lshlrev_b32_e32 v148, 16, v57
	v_and_b32_e32 v149, 0xffff0000, v57
	v_lshlrev_b32_e32 v150, 16, v58
	v_and_b32_e32 v151, 0xffff0000, v58
	v_lshlrev_b32_e32 v152, 16, v59
	v_and_b32_e32 v153, 0xffff0000, v59
	v_lshlrev_b32_e32 v154, 16, v60
	v_and_b32_e32 v155, 0xffff0000, v60
	v_lshlrev_b32_e32 v156, 16, v61
	v_and_b32_e32 v157, 0xffff0000, v61
	v_lshlrev_b32_e32 v158, 16, v62
	v_and_b32_e32 v159, 0xffff0000, v62
	v_lshlrev_b32_e32 v160, 16, v63
	v_and_b32_e32 v161, 0xffff0000, v63
	ds_swizzle_b32 v165, v164 offset:swizzle(SWAP,1)
	s_waitcnt lgkmcnt(0)
; DI unsigned cvtpk(float lo, float hi) { unsigned r; asm volatile("v_cvt_pk_bf16_f32 %0, %1, %2" : "=v"(r) : "v"(lo), "v"(hi)); return r; }
; template <bool XINB, bool XOUTB> DI void row_resid_norm(const bf16* trow, const bf16* trow2, int npart, const void* xin, void* xout, const float* gpost, float* rstd_out, int lane) {
;     ...
;   const float rstd = rsqrtf(wave_sum(s) * (1.f / DM) + EPS);
;   float s2 = 0.f;
; #pragma unroll
;   for (int j = 0; j < 8; ++j) { const f32x4 gg = gr[64 * j]; x[j] = x[j] + t[j] * rstd * gg; s2 += (x[j].x * x[j].x + x[j].y * x[j].y) + (x[j].z * x[j].z + x[j].w * x[j].w); }
;   asm volatile("s_waitcnt vmcnt(0)" ::: "memory");
; #pragma unroll
;   for (int j = 0; j < 8; ++j) { if (XOUTB) { u32x2 w; w.x = cvtpk(x[j].x, x[j].y); w.y = cvtpk(x[j].z, x[j].w); ((u32x2*)xout + lane)[64 * j] = w; } else ((f32x4*)xout + lane)[64 * j] = x[j]; }
	v_add_f32_e32 v164, v164, v165
	ds_swizzle_b32 v165, v164 offset:swizzle(SWAP,2)
	s_waitcnt lgkmcnt(0)
	v_add_f32_e32 v164, v164, v165
	ds_swizzle_b32 v165, v164 offset:swizzle(SWAP,4)
	s_waitcnt lgkmcnt(0)
	v_add_f32_e32 v164, v164, v165
	ds_swizzle_b32 v165, v164 offset:swizzle(SWAP,8)
	s_waitcnt lgkmcnt(0)
	v_add_f32_e32 v164, v164, v165
	ds_swizzle_b32 v165, v164 offset:swizzle(SWAP,16)
	s_waitcnt lgkmcnt(0)
	v_add_f32_e32 v164, v164, v165
	v_mov_b32_e32 v165, v164
	s_nop 1
	v_permlane32_swap_b32_e32 v164, v165
	v_add_f32_e32 v164, v164, v165
	v_fmamk_f32 v166, v164, 0x3a000000, v180
	v_rsq_f32_e32 v166, v166
	s_nop 0
	v_pk_mul_f32 v[96:97], v[96:97], v[166:167] op_sel_hi:[1,0]
	v_pk_mul_f32 v[98:99], v[98:99], v[166:167] op_sel_hi:[1,0]
	v_pk_mul_f32 v[100:101], v[100:101], v[166:167] op_sel_hi:[1,0]
	v_pk_mul_f32 v[102:103], v[102:103], v[166:167] op_sel_hi:[1,0]
	v_pk_mul_f32 v[104:105], v[104:105], v[166:167] op_sel_hi:[1,0]
	v_pk_mul_f32 v[106:107], v[106:107], v[166:167] op_sel_hi:[1,0]
	v_pk_mul_f32 v[108:109], v[108:109], v[166:167] op_sel_hi:[1,0]
	v_pk_mul_f32 v[110:111], v[110:111], v[166:167] op_sel_hi:[1,0]
	v_pk_mul_f32 v[114:115], v[114:115], v[166:167] op_sel_hi:[1,0]
	v_pk_mul_f32 v[116:117], v[116:117], v[166:167] op_sel_hi:[1,0]
	v_pk_mul_f32 v[118:119], v[118:119], v[166:167] op_sel_hi:[1,0]
	v_pk_mul_f32 v[120:121], v[120:121], v[166:167] op_sel_hi:[1,0]
	v_pk_mul_f32 v[122:123], v[122:123], v[166:167] op_sel_hi:[1,0]
	v_pk_mul_f32 v[124:125], v[124:125], v[166:167] op_sel_hi:[1,0]
	v_pk_mul_f32 v[126:127], v[126:127], v[166:167] op_sel_hi:[1,0]
	v_pk_mul_f32 v[128:129], v[128:129], v[166:167] op_sel_hi:[1,0]
	v_pk_fma_f32 v[130:131], v[0:1], v[96:97], v[130:131]
	v_pk_fma_f32 v[132:133], v[2:3], v[98:99], v[132:133]
	v_pk_fma_f32 v[134:135], v[4:5], v[100:101], v[134:135]
	v_pk_fma_f32 v[136:137], v[6:7], v[102:103], v[136:137]
	v_pk_fma_f32 v[138:139], v[8:9], v[104:105], v[138:139]
	v_pk_fma_f32 v[140:141], v[10:11], v[106:107], v[140:141]
	v_pk_fma_f32 v[142:143], v[12:13], v[108:109], v[142:143]
	v_pk_fma_f32 v[144:145], v[14:15], v[110:111], v[144:145]
	v_pk_fma_f32 v[146:147], v[16:17], v[114:115], v[146:147]
	v_pk_fma_f32 v[148:149], v[18:19], v[116:117], v[148:149]
	v_pk_fma_f32 v[150:151], v[20:21], v[118:119], v[150:151]
	v_pk_fma_f32 v[152:153], v[22:23], v[120:121], v[152:153]
	v_pk_fma_f32 v[154:155], v[24:25], v[122:123], v[154:155]
	v_pk_fma_f32 v[156:157], v[26:27], v[124:125], v[156:157]
	v_pk_fma_f32 v[158:159], v[28:29], v[126:127], v[158:159]
	v_pk_fma_f32 v[160:161], v[30:31], v[128:129], v[160:161]
	s_bitcmp1_b32 s11, 0
	s_cbranch_scc0 .Lrp_b_bf16
	s_add_u32 s12, s4, 0xfffff000
	s_addc_u32 s13, s5, -1
	global_store_dwordx4 v163, v[130:133], s[12:13] offset:0
	global_store_dwordx4 v163, v[134:137], s[12:13] offset:16
	global_store_dwordx4 v163, v[138:141], s[12:13] offset:2048
	global_store_dwordx4 v163, v[142:145], s[12:13] offset:2064
	global_store_dwordx4 v163, v[146:149], s[4:5] offset:0
	global_store_dwordx4 v163, v[150:153], s[4:5] offset:16
	global_store_dwordx4 v163, v[154:157], s[4:5] offset:2048
	global_store_dwordx4 v163, v[158:161], s[4:5] offset:2064
	s_branch .Lrp_b_stored

; DI bf16* xb_row(float* outp, int m) { return (bf16*)((char*)outp + (size_t)m * 8192 + 4096); }
; __global__ void __launch_bounds__(512) fwd_mega(Args a_) {
;     ...
;     } else if (ph == 4) {
;       for (int m = gw; m < MT; m += NGW)
;         row_resid_norm<true, true>((const bf16*)(ws + A_T) + (size_t)m * DM, (const bf16*)(ws + A_Q0) + (size_t)(m - NPR) * DM, (tail8 && m >= NPR) ? 8 : 0, xb_row(outp, m), xb_row(outp, m), a.in[7], (float*)(ws + A_RSTD) + m, lane);
;     } else if (ph == 16) {
;       for (int m = gw; m < MT; m += NGW)
;         row_resid_norm<true, true>((const bf16*)(ws + A_T) + (size_t)m * DM, (const bf16*)(ws + A_QM) + (size_t)(m - NPR) * DM, (tail8 && m >= NPR) ? 8 : 0, xb_row(outp, m), xb_row(outp, m), a.in[7] + DM, (float*)(ws + A_RSTD) + m, lane);
;     } else if (ph == 19) {
;       for (int m = gw; m < MT; m += NGW)
;         row_resid_norm<true, false>((const bf16*)(ws + A_T) + (size_t)m * DM, tail8 ? (const bf16*)(ws + A_PF) + (size_t)(m - NPR) * DM : (const bf16*)(ws + A_H) + (size_t)m * DM, tail8 ? (m < NPR ? 0 : 8) : 1, xb_row(outp, m), outp + (size_t)m * DM, a.in[9] + DM, nullptr, lane);
.Lrp_b_norstd:
	s_nop 1
.Lrp_done:
	s_mov_b64 exec, -1
	v_readlane_b32 s0, v255, 35
	s_cmp_eq_u32 s0, 4
	s_cbranch_scc1 .LBB0_235
	s_cmp_eq_u32 s0, 7
	s_cbranch_scc1 .LBB0_428
	s_cmp_eq_u32 s0, 16
	s_cbranch_scc1 .LBB0_179
	s_branch .LBB0_125

; DI bf16* xb_row(float* outp, int m) { return (bf16*)((char*)outp + (size_t)m * 8192 + 4096); }
; __global__ void __launch_bounds__(512) fwd_mega(Args a_) {
;     ...
;     } else if (ph == 16) {
;       for (int m = gw; m < MT; m += NGW)
;         row_resid_norm<true, true>((const bf16*)(ws + A_T) + (size_t)m * DM, (const bf16*)(ws + A_QM) + (size_t)(m - NPR) * DM, (tail8 && m >= NPR) ? 8 : 0, xb_row(outp, m), xb_row(outp, m), a.in[7] + DM, (float*)(ws + A_RSTD) + m, lane);
.LBB0_127:
	s_and_b64 vcc, exec, s[8:9]
	s_cbranch_vccz .LBB0_166
	v_readlane_b32 s0, v255, 35
	s_cmp_eq_u32 s0, 16
	s_mov_b64 s[6:7], -1
	s_cbranch_scc0 .LBB0_166
	s_cmpk_gt_i32 s72, 0x43ff
	s_cbranch_scc1 .LBB0_179
	s_and_b64 vcc, exec, s[78:79]
	s_cbranch_vccz .Lrp_orig16
	s_load_dwordx2 s[6:7], s[22:23], 0x38
	s_mov_b32 s10, 0x13400000
	s_mov_b32 s11, 2
	s_waitcnt lgkmcnt(0)
	s_add_u32 s6, s6, 0x2000
	s_addc_u32 s7, s7, 0
	s_branch .Lrp_entry
.Lrp_orig16:
	s_load_dwordx2 s[0:1], s[22:23], 0x38
	v_lshlrev_b32_e32 v112, 3, v186
	v_lshl_add_u64 v[0:1], s[54:55], 0, v[112:113]
	s_mov_b64 s[2:3], 0x13400000
	v_lshl_add_u64 v[4:5], v[0:1], 0, s[2:3]
	v_lshlrev_b32_e32 v0, 4, v186
	v_mov_b32_e32 v1, v113
	s_waitcnt lgkmcnt(0)
	v_lshl_add_u64 v[0:1], s[0:1], 0, v[0:1]
	s_mov_b64 s[0:1], 0x2000
	v_lshl_add_u64 v[6:7], v[0:1], 0, s[0:1]
	s_mov_b64 s[0:1], 0x3000
	v_lshl_add_u64 v[8:9], v[0:1], 0, s[0:1]
	s_mov_b64 s[0:1], 0x3400
	v_lshl_add_u64 v[10:11], v[0:1], 0, s[0:1]
	s_mov_b64 s[0:1], 0x3800
	v_lshl_add_u64 v[12:13], v[0:1], 0, s[0:1]
	s_mov_b64 s[0:1], 0x3c00
	s_ashr_i32 s73, s72, 31
	v_lshl_add_u64 v[14:15], v[0:1], 0, s[0:1]
	s_lshl_b64 s[0:1], s[72:73], 13
	s_add_u32 s6, s52, s0
	s_addc_u32 s7, s53, s1
	s_lshl_b64 s[0:1], s[72:73], 2
	s_add_u32 s8, s96, s0
	s_addc_u32 s9, s97, s1
	s_lshl_b64 s[0:1], s[72:73], 12
	s_add_u32 s10, s54, s0
	v_cmp_eq_u32_e64 s[42:43], 0, v186
	s_addc_u32 s11, s55, s1
	s_mov_b32 s0, s72
	s_branch .LBB0_132

; DI bf16* xb_row(float* outp, int m) { return (bf16*)((char*)outp + (size_t)m * 8192 + 4096); }
; __global__ void __launch_bounds__(512) fwd_mega(Args a_) {
;     ...
;     } else if (ph == 4) {
;       for (int m = gw; m < MT; m += NGW)
;         row_resid_norm<true, true>((const bf16*)(ws + A_T) + (size_t)m * DM, (const bf16*)(ws + A_Q0) + (size_t)(m - NPR) * DM, (tail8 && m >= NPR) ? 8 : 0, xb_row(outp, m), xb_row(outp, m), a.in[7], (float*)(ws + A_RSTD) + m, lane);
.LBB0_195:
	v_readlane_b32 s0, v255, 35
	s_cmp_gt_i32 s0, 1
	s_mov_b64 s[8:9], -1
	s_cbranch_scc0 .LBB0_311
	s_cmp_gt_i32 s0, 3
	s_cbranch_scc0 .LBB0_237
	v_readlane_b32 s0, v255, 35
	s_cmp_eq_u32 s0, 4
	s_mov_b64 s[6:7], -1
	s_cbranch_scc0 .LBB0_236
	s_cmpk_gt_i32 s72, 0x43ff
	s_cbranch_scc1 .LBB0_235
	s_and_b64 vcc, exec, s[78:79]
	s_cbranch_vccz .Lrp_orig4
	s_load_dwordx2 s[6:7], s[22:23], 0x38
	s_mov_b32 s10, 0xfc00000
	s_mov_b32 s11, 2
	s_waitcnt lgkmcnt(0)
	s_branch .Lrp_entry
.Lrp_orig4:
	s_load_dwordx2 s[0:1], s[22:23], 0x38
	v_lshlrev_b32_e32 v112, 3, v186
	v_lshl_add_u64 v[0:1], s[54:55], 0, v[112:113]
	s_mov_b64 s[2:3], 0xfc00000
	v_lshl_add_u64 v[4:5], v[0:1], 0, s[2:3]
	v_lshlrev_b32_e32 v0, 4, v186
	v_mov_b32_e32 v1, v113
	s_waitcnt lgkmcnt(0)
	v_lshl_add_u64 v[6:7], s[0:1], 0, v[0:1]
	s_mov_b64 s[0:1], 0x1000
	v_lshl_add_u64 v[8:9], v[6:7], 0, s[0:1]
	s_mov_b64 s[0:1], 0x1400
	v_lshl_add_u64 v[10:11], v[6:7], 0, s[0:1]
	s_mov_b64 s[0:1], 0x1800
	v_lshl_add_u64 v[12:13], v[6:7], 0, s[0:1]
	s_mov_b64 s[0:1], 0x1c00
	s_ashr_i32 s73, s72, 31
	v_lshl_add_u64 v[14:15], v[6:7], 0, s[0:1]
	s_lshl_b64 s[0:1], s[72:73], 13
	s_add_u32 s6, s52, s0
	s_addc_u32 s7, s53, s1
	s_lshl_b64 s[0:1], s[72:73], 2
	s_add_u32 s8, s96, s0
	s_addc_u32 s9, s97, s1
	s_lshl_b64 s[0:1], s[72:73], 12
	s_add_u32 s10, s54, s0
	v_cmp_eq_u32_e64 s[42:43], 0, v186
	s_addc_u32 s11, s55, s1
	s_mov_b32 s0, s72
	s_branch .LBB0_201

; #define LAS __attribute__((address_space(3)))
; template <bool BAND> DI void partialSM(f32x16& p0, f32x16& p1, float& m_reg, float& mn, float& alpha, bool masked, const LAS float* tb, float C) {
;     ...
;   const float mnC = -mn * CC;
; #pragma unroll
;   for (int r = 0; r < 16; ++r) p0[r] = fmaf(p0[r], CC, mnC);
; #pragma unroll
;   for (int r = 0; r < 16; ++r) p1[r] = fmaf(p1[r], CC, mnC);
; #pragma unroll
;   for (int r = 0; r < 16; ++r) p0[r] = __builtin_amdgcn_exp2f(p0[r]);
; }
; DI void finishSM(f32x16& p0, f32x16& p1, float alpha, float& l_reg, bf16x8& pa0, bf16x8& pa1, bf16x8& pa2, bf16x8& pa3) {
; #pragma unroll
;   for (int r = 0; r < 16; ++r) p1[r] = __builtin_amdgcn_exp2f(p1[r]);
;   float ps = 0;
; #pragma unroll
;   for (int r = 0; r < 16; ++r) ps += p0[r];
; #pragma unroll
;   for (int r = 0; r < 16; ++r) ps += p1[r];
;   { auto rr = __builtin_amdgcn_permlane32_swap(__float_as_uint(ps), __float_as_uint(ps), false, false);
;     ps = __uint_as_float(rr[0]) + __uint_as_float(rr[1]); }
;   l_reg = l_reg * alpha + ps;
;     ...
;   PK4(p0, 0, pa0); PK4(p0, 8, pa1); PK4(p1, 0, pa2); PK4(p1, 8, pa3);
;     ...
; }
; template <int NQ> DI void qkt(f32x16& p0, f32x16& p1, const LAS char* Ks, const LAS char* KRs, const bf16x8* qr, int r32, int hi) {
;   p0 = f32x16{}; p1 = f32x16{};
; #pragma unroll
;   for (int d0 = 0; d0 < 8; ++d0) { const int cb = (d0 * 16 + hi * 8) * 2;
;     const bf16x8 b0 = *(const LAS bf16x8*)(Ks + KSWZ(r32, cb));
;     const bf16x8 b1 = *(const LAS bf16x8*)(Ks + KSWZ(32 + r32, cb));
;     p0 = __builtin_amdgcn_mfma_f32_32x32x16_bf16(b0, qr[d0], p0, 0, 0, 0);
;     p1 = __builtin_amdgcn_mfma_f32_32x32x16_bf16(b1, qr[d0], p1, 0, 0, 0); }
;   if (NQ == 12) {
; #pragma unroll
;     for (int d0 = 0; d0 < 4; ++d0) { const int cb = (d0 * 16 + hi * 8) * 2;
;       const bf16x8 b0 = *(const LAS bf16x8*)(KRs + KRSWZ(r32, cb));
;       const bf16x8 b1 = *(const LAS bf16x8*)(KRs + KRSWZ(32 + r32, cb));
;       p0 = __builtin_amdgcn_mfma_f32_32x32x16_bf16(b0, qr[8 + d0], p0, 0, 0, 0);
;       p1 = __builtin_amdgcn_mfma_f32_32x32x16_bf16(b1, qr[8 + d0], p1, 0, 0, 0); }
;   }
; }
.LBB0_349:
	v_mul_f32_e32 v176, 0xbdd53b94, v203
	v_fmamk_f32 v64, v74, 0x3dd53b94, v176
	v_fmamk_f32 v65, v75, 0x3dd53b94, v176
	v_fmamk_f32 v66, v76, 0x3dd53b94, v176
	v_fmamk_f32 v67, v77, 0x3dd53b94, v176
	v_fmamk_f32 v68, v78, 0x3dd53b94, v176
	v_fmamk_f32 v69, v79, 0x3dd53b94, v176
	v_fmamk_f32 v70, v80, 0x3dd53b94, v176
	v_fmamk_f32 v71, v81, 0x3dd53b94, v176
	v_fmamk_f32 v74, v82, 0x3dd53b94, v176
	v_fmamk_f32 v75, v83, 0x3dd53b94, v176
	v_fmamk_f32 v76, v84, 0x3dd53b94, v176
	v_fmamk_f32 v77, v85, 0x3dd53b94, v176
	v_fmamk_f32 v78, v86, 0x3dd53b94, v176
	v_fmamk_f32 v79, v87, 0x3dd53b94, v176
	v_fmamk_f32 v80, v88, 0x3dd53b94, v176
	v_fmamk_f32 v81, v89, 0x3dd53b94, v176
	v_fmamk_f32 v167, v96, 0x3dd53b94, v176
	v_fmamk_f32 v168, v97, 0x3dd53b94, v176
	v_fmamk_f32 v169, v98, 0x3dd53b94, v176
	v_fmamk_f32 v170, v99, 0x3dd53b94, v176
	v_fmamk_f32 v171, v100, 0x3dd53b94, v176
	v_fmamk_f32 v172, v101, 0x3dd53b94, v176
	v_fmamk_f32 v165, v104, 0x3dd53b94, v176
	v_exp_f32_e32 v110, v64
	v_exp_f32_e32 v164, v65
	v_exp_f32_e32 v108, v66
	v_exp_f32_e32 v111, v67
	v_exp_f32_e32 v107, v68
	v_exp_f32_e32 v109, v69
	v_exp_f32_e32 v105, v70
	v_exp_f32_e32 v106, v71
	v_exp_f32_e32 v101, v74
	v_exp_f32_e32 v104, v75
	v_exp_f32_e32 v100, v76
	v_exp_f32_e32 v103, v77
	v_exp_f32_e32 v97, v78
	v_exp_f32_e32 v99, v79
	v_exp_f32_e32 v96, v80
	v_exp_f32_e32 v98, v81
	v_fmamk_f32 v177, v93, 0x3dd53b94, v176
	v_fmamk_f32 v166, v95, 0x3dd53b94, v176
	v_fmamk_f32 v102, v102, 0x3dd53b94, v176
	v_fmamk_f32 v173, v90, 0x3dd53b94, v176
	v_fmamk_f32 v174, v91, 0x3dd53b94, v176
	v_fmamk_f32 v175, v92, 0x3dd53b94, v176
	v_fmamk_f32 v179, v94, 0x3dd53b94, v176
	v_fmamk_f32 v196, v72, 0x3dd53b94, v176
	v_fmamk_f32 v197, v73, 0x3dd53b94, v176
	s_waitcnt lgkmcnt(0)
	s_barrier
	ds_read_b128 v[80:83], v207 offset:41472
	ds_read_b128 v[64:67], v207 offset:32768
	ds_read_b128 v[212:215], v207 offset:32800
	ds_read_b128 v[224:227], v207 offset:41504
	v_exp_f32_e32 v177, v177
	s_waitcnt lgkmcnt(3)
	v_mfma_f32_32x32x16_bf16 v[80:95], v[80:83], v[160:163], 0
	v_exp_f32_e32 v179, v179
	v_exp_f32_e32 v166, v166
	v_exp_f32_e32 v167, v167
	v_exp_f32_e32 v165, v165
	v_exp_f32_e32 v102, v102
	v_exp_f32_e32 v196, v196
	v_exp_f32_e32 v197, v197
	s_waitcnt lgkmcnt(2)
	v_mfma_f32_32x32x16_bf16 v[64:79], v[64:67], v[160:163], 0
	s_waitcnt lgkmcnt(1)
	v_mfma_f32_32x32x16_bf16 v[64:79], v[212:215], v[156:159], v[64:79]
	s_waitcnt lgkmcnt(0)
	v_mfma_f32_32x32x16_bf16 v[80:95], v[224:227], v[156:159], v[80:95]
	ds_read_b128 v[212:215], v207 offset:32832
	ds_read_b128 v[224:227], v207 offset:41536
	s_waitcnt lgkmcnt(1)
	v_mfma_f32_32x32x16_bf16 v[64:79], v[212:215], v[152:155], v[64:79]
	s_waitcnt lgkmcnt(0)
	v_mfma_f32_32x32x16_bf16 v[80:95], v[224:227], v[152:155], v[80:95]
	ds_read_b128 v[212:215], v207 offset:32864
	ds_read_b128 v[224:227], v207 offset:41568
	s_waitcnt lgkmcnt(1)
	v_mfma_f32_32x32x16_bf16 v[64:79], v[212:215], v[148:151], v[64:79]
	s_waitcnt lgkmcnt(0)
	v_mfma_f32_32x32x16_bf16 v[80:95], v[224:227], v[148:151], v[80:95]
	ds_read_b128 v[212:215], v207 offset:32896
	ds_read_b128 v[224:227], v207 offset:41600
	s_waitcnt lgkmcnt(1)
	v_mfma_f32_32x32x16_bf16 v[64:79], v[212:215], v[144:147], v[64:79]
	s_waitcnt lgkmcnt(0)
	v_mfma_f32_32x32x16_bf16 v[80:95], v[224:227], v[144:147], v[80:95]
	ds_read_b128 v[212:215], v207 offset:32928
	ds_read_b128 v[224:227], v207 offset:41632
	s_waitcnt lgkmcnt(1)
	v_mfma_f32_32x32x16_bf16 v[64:79], v[212:215], v[140:143], v[64:79]
	s_waitcnt lgkmcnt(0)
	v_mfma_f32_32x32x16_bf16 v[80:95], v[224:227], v[140:143], v[80:95]
	ds_read_b128 v[212:215], v207 offset:32960
	ds_read_b128 v[224:227], v207 offset:41664
	s_waitcnt lgkmcnt(1)
	v_mfma_f32_32x32x16_bf16 v[64:79], v[212:215], v[136:139], v[64:79]
	s_waitcnt lgkmcnt(0)
	v_mfma_f32_32x32x16_bf16 v[80:95], v[224:227], v[136:139], v[80:95]
	ds_read_b128 v[212:215], v207 offset:32992
	ds_read_b128 v[224:227], v207 offset:41696
	s_waitcnt lgkmcnt(1)
	v_mfma_f32_32x32x16_bf16 v[64:79], v[212:215], v[132:135], v[64:79]
	s_waitcnt lgkmcnt(0)
	v_mfma_f32_32x32x16_bf16 v[80:95], v[224:227], v[132:135], v[80:95]
	ds_read_b128 v[212:215], v217 offset:4608
	ds_read_b128 v[224:227], v217
	ds_read_b128 v[228:231], v217 offset:32
	s_waitcnt lgkmcnt(1)
	v_mfma_f32_32x32x16_bf16 v[64:79], v[224:227], v[128:131], v[64:79]
	v_mfma_f32_32x32x16_bf16 v[80:95], v[212:215], v[128:131], v[80:95]
	ds_read_b128 v[212:215], v217 offset:4640
	s_waitcnt lgkmcnt(1)
	v_mfma_f32_32x32x16_bf16 v[64:79], v[228:231], v[124:127], v[64:79]
	v_exp_f32_e32 v228, v172
	s_waitcnt lgkmcnt(0)
	v_mfma_f32_32x32x16_bf16 v[80:95], v[212:215], v[124:127], v[80:95]
	ds_read_b128 v[212:215], v217 offset:64
	ds_read_b128 v[224:227], v217 offset:4672
	s_waitcnt lgkmcnt(1)
	v_mfma_f32_32x32x16_bf16 v[64:79], v[212:215], v[120:123], v[64:79]
	s_waitcnt lgkmcnt(0)
	v_mfma_f32_32x32x16_bf16 v[80:95], v[224:227], v[120:123], v[80:95]
	ds_read_b128 v[212:215], v217 offset:96
	ds_read_b128 v[224:227], v217 offset:4704
	s_waitcnt lgkmcnt(1)
	v_mfma_f32_32x32x16_bf16 v[64:79], v[212:215], v[116:119], v[64:79]
	v_exp_f32_e32 v215, v168
	v_add_f32_e32 v168, 0, v110
	v_add_f32_e32 v168, v164, v168
	v_add_f32_e32 v168, v108, v168
	v_add_f32_e32 v168, v111, v168
	v_add_f32_e32 v168, v107, v168
	v_add_f32_e32 v168, v109, v168
	v_add_f32_e32 v168, v105, v168
	v_add_f32_e32 v168, v106, v168
	v_add_f32_e32 v168, v101, v168
	v_add_f32_e32 v168, v104, v168
	v_add_f32_e32 v168, v100, v168
	v_add_f32_e32 v168, v103, v168
	v_exp_f32_e32 v212, v173
	v_add_f32_e32 v168, v97, v168
	v_exp_f32_e32 v213, v174
	v_add_f32_e32 v168, v99, v168
	v_exp_f32_e32 v214, v175
	v_add_f32_e32 v168, v96, v168
	v_add_f32_e32 v168, v98, v168
	v_add_f32_e32 v168, v212, v168
	v_add_f32_e32 v168, v213, v168
	v_add_f32_e32 v168, v214, v168
	v_add_f32_e32 v168, v177, v168
	s_waitcnt lgkmcnt(0)
; #define SBAR() __builtin_amdgcn_sched_barrier(0)
; template <int OFF> DI s16x4 tr_read(int vb) { s16x4 r; asm volatile("ds_read_b64_tr_b16 %0, %1 offset:%2" : "=&v"(r) : "v"(vb), "i"(OFF) : "memory"); return r; }
; DI void finishSM(f32x16& p0, f32x16& p1, float alpha, float& l_reg, bf16x8& pa0, bf16x8& pa1, bf16x8& pa2, bf16x8& pa3) {
; #pragma unroll
;   for (int r = 0; r < 16; ++r) p1[r] = __builtin_amdgcn_exp2f(p1[r]);
;   float ps = 0;
; #pragma unroll
;   for (int r = 0; r < 16; ++r) ps += p0[r];
; #pragma unroll
;   for (int r = 0; r < 16; ++r) ps += p1[r];
;   { auto rr = __builtin_amdgcn_permlane32_swap(__float_as_uint(ps), __float_as_uint(ps), false, false);
;     ps = __uint_as_float(rr[0]) + __uint_as_float(rr[1]); }
;   l_reg = l_reg * alpha + ps;
;     ...
;   PK4(p0, 0, pa0); PK4(p0, 8, pa1); PK4(p1, 0, pa2); PK4(p1, 8, pa3);
;     ...
; }
; template <int D0> DI void pv_one(f32x16& od, int vb, bf16x8 pa0, bf16x8 pa1, bf16x8 pa2, bf16x8 pa3) {
;   const s16x4 l0 = tr_read<v_rd_off(D0, 0, 0)>(vb), h0 = tr_read<v_rd_off(D0, 0, 1)>(vb), l1 = tr_read<v_rd_off(D0, 1, 0)>(vb), h1 = tr_read<v_rd_off(D0, 1, 1)>(vb);
;   const s16x4 l2 = tr_read<v_rd_off(D0, 2, 0)>(vb), h2 = tr_read<v_rd_off(D0, 2, 1)>(vb), l3 = tr_read<v_rd_off(D0, 3, 0)>(vb), h3 = tr_read<v_rd_off(D0, 3, 1)>(vb);
;   asm volatile("s_waitcnt lgkmcnt(0)" ::: "memory"); SBAR();
;     ...
;   od = __builtin_amdgcn_mfma_f32_32x32x16_bf16(pa0, PK(l0, h0), od, 0, 0, 0);
;   od = __builtin_amdgcn_mfma_f32_32x32x16_bf16(pa1, PK(l1, h1), od, 0, 0, 0);
;   od = __builtin_amdgcn_mfma_f32_32x32x16_bf16(pa2, PK(l2, h2), od, 0, 0, 0);
;   od = __builtin_amdgcn_mfma_f32_32x32x16_bf16(pa3, PK(l3, h3), od, 0, 0, 0);
;     ...
; }
; DI void pv_d0(f32x16* o, int vb, bf16x8 pa0, bf16x8 pa1, bf16x8 pa2, bf16x8 pa3) {
;   pv_one<0>(o[0], vb, pa0, pa1, pa2, pa3); pv_one<1>(o[1], vb, pa0, pa1, pa2, pa3); pv_one<2>(o[2], vb, pa0, pa1, pa2, pa3); pv_one<3>(o[3], vb, pa0, pa1, pa2, pa3);
	v_mfma_f32_32x32x16_bf16 v[80:95], v[224:227], v[116:119], v[80:95]
	v_exp_f32_e32 v225, v169
	v_add_f32_e32 v168, v179, v168
	v_exp_f32_e32 v226, v170
	v_add_f32_e32 v168, v166, v168
	v_exp_f32_e32 v227, v171
	v_add_f32_e32 v168, v167, v168
	v_add_f32_e32 v168, v215, v168
	v_add_f32_e32 v168, v225, v168
	v_add_f32_e32 v168, v226, v168
	v_add_f32_e32 v168, v227, v168
	v_add_f32_e32 v168, v228, v168
	v_add_f32_e32 v168, v165, v168
	v_add_f32_e32 v168, v102, v168
	v_add_f32_e32 v168, v196, v168
	v_add_f32_e32 v223, v197, v168
	v_mov_b32_e32 v224, v223
	v_cvt_pk_bf16_f32 v168, v110, v164
	v_cvt_pk_bf16_f32 v169, v108, v111
	v_cvt_pk_bf16_f32 v170, v107, v109
	s_nop 1
	v_permlane32_swap_b32_e32 v223, v224
	v_cvt_pk_bf16_f32 v171, v105, v106
	v_permlane32_swap_b32_e32 v168, v170
	v_cvt_pk_bf16_f32 v172, v101, v104
	v_cvt_pk_bf16_f32 v173, v100, v103
	v_cvt_pk_bf16_f32 v174, v97, v99
	v_cvt_pk_bf16_f32 v175, v96, v98
	v_cvt_pk_bf16_f32 v212, v212, v213
	v_cvt_pk_bf16_f32 v213, v214, v177
	v_cvt_pk_bf16_f32 v214, v179, v166
	v_cvt_pk_bf16_f32 v215, v167, v215
	v_cvt_pk_bf16_f32 v226, v225, v226
	v_cvt_pk_bf16_f32 v227, v227, v228
	v_cvt_pk_bf16_f32 v228, v165, v102
	v_cvt_pk_bf16_f32 v229, v196, v197
	v_permlane32_swap_b32_e32 v169, v171
	v_permlane32_swap_b32_e32 v172, v174
	v_permlane32_swap_b32_e32 v173, v175
	v_permlane32_swap_b32_e32 v212, v214
	v_permlane32_swap_b32_e32 v213, v215
	v_permlane32_swap_b32_e32 v226, v228
	v_permlane32_swap_b32_e32 v227, v229
	s_min_i32 s16, s35, s33
	s_ashr_i32 s17, s16, 31
	s_lshl_b64 s[22:23], s[16:17], 19
	s_add_u32 s40, s12, s22
	s_addc_u32 s41, s13, s23
	s_add_u32 s22, s14, s22
	s_addc_u32 s23, s15, s23
	s_lshl_b64 s[16:17], s[16:17], 13
	v_lshl_add_u64 v[96:97], s[22:23], 0, v[112:113]
	v_lshl_add_u64 v[100:101], s[22:23], 0, v[114:115]
	v_lshl_add_u64 v[104:105], s[40:41], 0, v[112:113]
	v_lshl_add_u64 v[108:109], s[40:41], 0, v[114:115]
	v_lshl_add_u64 v[164:165], v[192:193], 0, s[16:17]
	global_load_dwordx4 v[96:99], v[96:97], off
	s_nop 0
	global_load_dwordx4 v[100:103], v[100:101], off
	s_nop 0
	global_load_dwordx4 v[104:107], v[104:105], off
	s_nop 0
	global_load_dwordx4 v[108:111], v[108:109], off
	s_nop 0
	global_load_dwordx4 v[164:167], v[164:165], off
	ds_read_b64_tr_b16 v[230:231], v202 offset:0
	ds_read_b64_tr_b16 v[232:233], v202 offset:0x800
	ds_read_b64_tr_b16 v[234:235], v202 offset:0x1000
	ds_read_b64_tr_b16 v[236:237], v202 offset:0x1800
	ds_read_b64_tr_b16 v[242:243], v202 offset:0x2000
	ds_read_b64_tr_b16 v[244:245], v202 offset:0x2800
	ds_read_b64_tr_b16 v[246:247], v202 offset:0x3000
	ds_read_b64_tr_b16 v[248:249], v202 offset:0x3800
	s_waitcnt lgkmcnt(0)
	s_nop 0
	v_mfma_f32_32x32x16_bf16 v[0:15], v[168:171], v[230:233], v[0:15]
	ds_read_b64_tr_b16 v[230:231], v202 offset:0x200
	ds_read_b64_tr_b16 v[232:233], v202 offset:0xa00
	v_mfma_f32_32x32x16_bf16 v[0:15], v[172:175], v[234:237], v[0:15]
	ds_read_b64_tr_b16 v[234:235], v202 offset:0x1200
	ds_read_b64_tr_b16 v[236:237], v202 offset:0x1a00
	v_mfma_f32_32x32x16_bf16 v[0:15], v[212:215], v[242:245], v[0:15]
	ds_read_b64_tr_b16 v[242:243], v202 offset:0x2200
	ds_read_b64_tr_b16 v[244:245], v202 offset:0x2a00
	v_mfma_f32_32x32x16_bf16 v[0:15], v[226:229], v[246:249], v[0:15]
	ds_read_b64_tr_b16 v[246:247], v202 offset:0x3200
	ds_read_b64_tr_b16 v[248:249], v202 offset:0x3a00
	s_waitcnt lgkmcnt(0)
; #define LAS __attribute__((address_space(3)))
; #define SBAR() __builtin_amdgcn_sched_barrier(0)
; template <bool BAND> DI void partialSM(f32x16& p0, f32x16& p1, float& m_reg, float& mn, float& alpha, bool masked, const LAS float* tb, float C) {
;   if (masked) {
; #pragma unroll
;     for (int r = 0; r < 16; ++r) { p0[r] = -1e30f; p1[r] = -1e30f; }
;   } else if (BAND) {
; #pragma unroll
;     for (int r = 0; r < 16; ++r) { const int ko = (r & 3) + 8 * (r >> 2); p0[r] = fmaf(p0[r], C, tb[ko]); }
;     SBAR();
; #pragma unroll
;     for (int r = 0; r < 16; ++r) { const int ko = (r & 3) + 8 * (r >> 2); p1[r] = fmaf(p1[r], C, tb[ko + 32]); }
;   }
;   const float CC = BAND ? 1.f : C;
;   const float THRP = 11.5f / CC;
;   float pmax = p0[0];
; #pragma unroll
;   for (int r = 1; r < 16; ++r) pmax = fmaxf(pmax, p0[r]);
; #pragma unroll
;   for (int r = 0; r < 16; ++r) pmax = fmaxf(pmax, p1[r]);
;   { auto rr = __builtin_amdgcn_permlane32_swap(__float_as_uint(pmax), __float_as_uint(pmax), false, false);
;     pmax = fmaxf(__uint_as_float(rr[0]), __uint_as_float(rr[1])); }
;   if (__builtin_expect(__all(pmax - m_reg <= THRP), 1)) { mn = m_reg; alpha = 1.f; }
;   else { mn = fmaxf(m_reg, pmax); alpha = __builtin_amdgcn_exp2f((m_reg - mn) * CC); m_reg = mn; }
; template <int D0> DI void pv_one(f32x16& od, int vb, bf16x8 pa0, bf16x8 pa1, bf16x8 pa2, bf16x8 pa3) {
;   const s16x4 l0 = tr_read<v_rd_off(D0, 0, 0)>(vb), h0 = tr_read<v_rd_off(D0, 0, 1)>(vb), l1 = tr_read<v_rd_off(D0, 1, 0)>(vb), h1 = tr_read<v_rd_off(D0, 1, 1)>(vb);
;   const s16x4 l2 = tr_read<v_rd_off(D0, 2, 0)>(vb), h2 = tr_read<v_rd_off(D0, 2, 1)>(vb), l3 = tr_read<v_rd_off(D0, 3, 0)>(vb), h3 = tr_read<v_rd_off(D0, 3, 1)>(vb);
;   asm volatile("s_waitcnt lgkmcnt(0)" ::: "memory"); SBAR();
;     ...
;   od = __builtin_amdgcn_mfma_f32_32x32x16_bf16(pa0, PK(l0, h0), od, 0, 0, 0);
;   od = __builtin_amdgcn_mfma_f32_32x32x16_bf16(pa1, PK(l1, h1), od, 0, 0, 0);
;   od = __builtin_amdgcn_mfma_f32_32x32x16_bf16(pa2, PK(l2, h2), od, 0, 0, 0);
;   od = __builtin_amdgcn_mfma_f32_32x32x16_bf16(pa3, PK(l3, h3), od, 0, 0, 0);
;     ...
; }
; DI void pv_d0(f32x16* o, int vb, bf16x8 pa0, bf16x8 pa1, bf16x8 pa2, bf16x8 pa3) {
;   pv_one<0>(o[0], vb, pa0, pa1, pa2, pa3); pv_one<1>(o[1], vb, pa0, pa1, pa2, pa3); pv_one<2>(o[2], vb, pa0, pa1, pa2, pa3); pv_one<3>(o[3], vb, pa0, pa1, pa2, pa3);
	v_mfma_f32_32x32x16_bf16 v[48:63], v[168:171], v[230:233], v[48:63]
	ds_read_b64_tr_b16 v[230:231], v202 offset:0x400
	ds_read_b64_tr_b16 v[232:233], v202 offset:0xc00
	v_mfma_f32_32x32x16_bf16 v[48:63], v[172:175], v[234:237], v[48:63]
	ds_read_b64_tr_b16 v[234:235], v202 offset:0x1400
	ds_read_b64_tr_b16 v[236:237], v202 offset:0x1c00
	v_mfma_f32_32x32x16_bf16 v[48:63], v[212:215], v[242:245], v[48:63]
	ds_read_b64_tr_b16 v[242:243], v202 offset:0x2400
	ds_read_b64_tr_b16 v[244:245], v202 offset:0x2c00
	v_mfma_f32_32x32x16_bf16 v[48:63], v[226:229], v[246:249], v[48:63]
	ds_read_b64_tr_b16 v[246:247], v202 offset:0x3400
	ds_read_b64_tr_b16 v[248:249], v202 offset:0x3c00
	s_waitcnt lgkmcnt(0)
	v_mfma_f32_32x32x16_bf16 v[32:47], v[168:171], v[230:233], v[32:47]
	ds_read_b64_tr_b16 v[230:231], v202 offset:0x600
	ds_read_b64_tr_b16 v[232:233], v202 offset:0xe00
	v_mfma_f32_32x32x16_bf16 v[32:47], v[172:175], v[234:237], v[32:47]
	ds_read_b64_tr_b16 v[234:235], v202 offset:0x1600
	ds_read_b64_tr_b16 v[236:237], v202 offset:0x1e00
	v_mfma_f32_32x32x16_bf16 v[32:47], v[212:215], v[242:245], v[32:47]
	ds_read_b64_tr_b16 v[242:243], v202 offset:0x2600
	ds_read_b64_tr_b16 v[244:245], v202 offset:0x2e00
	v_mfma_f32_32x32x16_bf16 v[32:47], v[226:229], v[246:249], v[32:47]
	ds_read_b64_tr_b16 v[246:247], v202 offset:0x3600
	ds_read_b64_tr_b16 v[248:249], v202 offset:0x3e00
	s_waitcnt lgkmcnt(0)
	v_mfma_f32_32x32x16_bf16 v[16:31], v[168:171], v[230:233], v[16:31]
	s_cmp_gt_i32 s34, s39
	s_cselect_b64 s[16:17], -1, 0
	s_cmp_ge_i32 s37, s21
	s_cselect_b64 s[22:23], -1, 0
	s_or_b64 vcc, s[16:17], s[22:23]
	v_cndmask_b32_e32 v65, v65, v211, vcc
	v_cndmask_b32_e32 v64, v64, v211, vcc
	v_mfma_f32_32x32x16_bf16 v[16:31], v[172:175], v[234:237], v[16:31]
	v_max_f32_e32 v168, v65, v65
	v_max_f32_e32 v169, v64, v64
	v_cndmask_b32_e32 v67, v67, v211, vcc
	v_cndmask_b32_e32 v66, v66, v211, vcc
	v_max_f32_e32 v168, v169, v168
	v_cndmask_b32_e32 v69, v69, v211, vcc
	v_cndmask_b32_e32 v68, v68, v211, vcc
	v_max3_f32 v168, v168, v66, v67
	v_cndmask_b32_e32 v71, v71, v211, vcc
	v_cndmask_b32_e32 v70, v70, v211, vcc
	v_max3_f32 v168, v168, v68, v69
	v_cndmask_b32_e32 v73, v73, v211, vcc
	v_cndmask_b32_e32 v72, v72, v211, vcc
	v_max3_f32 v168, v168, v70, v71
	v_cndmask_b32_e32 v75, v75, v211, vcc
	v_cndmask_b32_e32 v74, v74, v211, vcc
	v_max3_f32 v168, v168, v72, v73
	v_cndmask_b32_e32 v77, v77, v211, vcc
	v_cndmask_b32_e32 v76, v76, v211, vcc
	v_max3_f32 v168, v168, v74, v75
	v_cndmask_b32_e32 v79, v79, v211, vcc
	v_cndmask_b32_e32 v78, v78, v211, vcc
	v_max3_f32 v168, v168, v76, v77
	v_mfma_f32_32x32x16_bf16 v[16:31], v[212:215], v[242:245], v[16:31]
	v_cndmask_b32_e32 v81, v81, v211, vcc
	v_cndmask_b32_e32 v80, v80, v211, vcc
	v_max3_f32 v168, v168, v78, v79
	v_cndmask_b32_e32 v83, v83, v211, vcc
	v_cndmask_b32_e32 v82, v82, v211, vcc
	v_max3_f32 v168, v168, v80, v81
	v_cndmask_b32_e32 v85, v85, v211, vcc
	v_cndmask_b32_e32 v84, v84, v211, vcc
	v_max3_f32 v168, v168, v82, v83
	v_cndmask_b32_e32 v87, v87, v211, vcc
	v_cndmask_b32_e32 v86, v86, v211, vcc
	v_max3_f32 v168, v168, v84, v85
	v_cndmask_b32_e32 v89, v89, v211, vcc
	v_cndmask_b32_e32 v88, v88, v211, vcc
	v_max3_f32 v168, v168, v86, v87
	v_cndmask_b32_e32 v91, v91, v211, vcc
	v_cndmask_b32_e32 v90, v90, v211, vcc
	v_max3_f32 v168, v168, v88, v89
	v_cndmask_b32_e32 v93, v93, v211, vcc
	v_cndmask_b32_e32 v92, v92, v211, vcc
	v_max3_f32 v168, v168, v90, v91
	v_cndmask_b32_e32 v95, v95, v211, vcc
	v_cndmask_b32_e32 v94, v94, v211, vcc
	v_max3_f32 v168, v168, v92, v93
	v_mfma_f32_32x32x16_bf16 v[16:31], v[226:229], v[246:249], v[16:31]
	v_max3_f32 v168, v168, v94, v95
	v_mov_b32_e32 v169, v168
	s_nop 1
	v_permlane32_swap_b32_e32 v168, v169
	v_max_f32_e32 v169, v169, v169
	v_max_f32_e32 v168, v168, v168
	v_max_f32_e32 v168, v168, v169
	v_sub_f32_e32 v169, v168, v203
	v_cmp_ge_f32_e32 vcc, s84, v169
	v_mov_b32_e32 v177, 1.0
	s_cmp_eq_u64 vcc, exec
	s_cbranch_scc0 .LBB0_357

; #define SBAR() __builtin_amdgcn_sched_barrier(0)
; #define SWAIT() do { if (SD == 2) asm volatile("s_waitcnt vmcnt(%0)" ::"n"(BAND ? 4 : 5) : "memory"); else asm volatile("s_waitcnt vmcnt(0)" ::: "memory"); } while (0)
; #define RESC(a) do { if (__any((a) < 1.f)) { if (hi == 0) al_l[r32] = (a); asm volatile("s_waitcnt lgkmcnt(0)" ::: "memory"); \
;     _Pragma("unroll") for (int d = 0; d < 4; ++d) _Pragma("unroll") for (int r = 0; r < 16; ++r) o[d][r] *= al_l[crow(r, hi)]; } } while (0)
; template <bool BAND> DI void partialSM(f32x16& p0, f32x16& p1, float& m_reg, float& mn, float& alpha, bool masked, const LAS float* tb, float C) {
;     ...
;   const float mnC = -mn * CC;
; #pragma unroll
;   for (int r = 0; r < 16; ++r) p0[r] = fmaf(p0[r], CC, mnC);
; #pragma unroll
;   for (int r = 0; r < 16; ++r) p1[r] = fmaf(p1[r], CC, mnC);
; #pragma unroll
;   for (int r = 0; r < 16; ++r) p0[r] = __builtin_amdgcn_exp2f(p0[r]);
; }
; DI void finishSM(f32x16& p0, f32x16& p1, float alpha, float& l_reg, bf16x8& pa0, bf16x8& pa1, bf16x8& pa2, bf16x8& pa3) {
; #pragma unroll
;   for (int r = 0; r < 16; ++r) p1[r] = __builtin_amdgcn_exp2f(p1[r]);
;   float ps = 0;
; #pragma unroll
;   for (int r = 0; r < 16; ++r) ps += p0[r];
; #pragma unroll
;   for (int r = 0; r < 16; ++r) ps += p1[r];
;   { auto rr = __builtin_amdgcn_permlane32_swap(__float_as_uint(ps), __float_as_uint(ps), false, false);
;     ps = __uint_as_float(rr[0]) + __uint_as_float(rr[1]); }
;   l_reg = l_reg * alpha + ps;
; template <bool BAND, int SD, bool ACT> DI void attn_unit_(const Unit& U, LAS char* lds, float C) {
;     ...
;     if (ACT) { qkt<NQ>(pA0, pA1, K_lds, KR_lds, qr, r32, hi); finishSM(pB0, pB1, alB, l_reg, pa0, pa1, pa2, pa3); }
;     SBAR();
;     if (SD == 1 || j + 3 < NT) SLOAD(SE, j + 1 + SD); SBAR();
;     if (ACT) { pv_d0(o, vb0 + SHM_V, pa0, pa1, pa2, pa3); partialSM<BAND>(pA0, pA1, m_reg, mnA, alA, MASKED(j + 1), T3 + jb0 + 64 * (j + 1), C); }
;     __syncthreads(); SWAIT(); SWRITE(1, SO);
;     if (ACT) RESC(alA);
;     __syncthreads();
.LBB0_354:
	v_mov_b32_e32 v98, v176
	v_fmamk_f32 v64, v64, 0x3dd53b94, v176
	v_fmamk_f32 v65, v65, 0x3dd53b94, v176
	v_fmamk_f32 v66, v66, 0x3dd53b94, v176
	v_fmamk_f32 v67, v67, 0x3dd53b94, v176
	v_fmamk_f32 v68, v68, 0x3dd53b94, v176
	v_fmamk_f32 v69, v69, 0x3dd53b94, v176
	v_fmamk_f32 v70, v70, 0x3dd53b94, v176
	v_fmamk_f32 v71, v71, 0x3dd53b94, v176
	v_fmamk_f32 v96, v72, 0x3dd53b94, v176
	v_fmamk_f32 v97, v73, 0x3dd53b94, v176
	v_fmamk_f32 v74, v74, 0x3dd53b94, v176
	v_fmamk_f32 v75, v75, 0x3dd53b94, v176
	v_fmamk_f32 v76, v76, 0x3dd53b94, v176
	v_fmamk_f32 v77, v77, 0x3dd53b94, v176
	v_fmamk_f32 v78, v78, 0x3dd53b94, v176
	v_fmac_f32_e32 v98, 0x3dd53b94, v79
	v_exp_f32_e32 v110, v64
	v_exp_f32_e32 v111, v65
	v_exp_f32_e32 v108, v66
	v_exp_f32_e32 v109, v67
	v_exp_f32_e32 v106, v68
	v_exp_f32_e32 v107, v69
	v_exp_f32_e32 v72, v70
	v_exp_f32_e32 v73, v71
	v_exp_f32_e32 v66, v96
	v_exp_f32_e32 v67, v97
	v_exp_f32_e32 v64, v74
	v_exp_f32_e32 v65, v75
	v_exp_f32_e32 v68, v76
	v_exp_f32_e32 v69, v77
	v_exp_f32_e32 v70, v78
	v_exp_f32_e32 v71, v98
	v_add_f32_e32 v74, v220, v221
	v_fmac_f32_e32 v74, v219, v201
	v_add_f32_e32 v201, v223, v224
	s_add_i32 s16, s35, 2
	s_add_i32 s17, s35, 1
	v_pk_fma_f32 v[196:197], v[80:81], s[38:39], v[176:177] op_sel_hi:[1,0,0]
	v_pk_fma_f32 v[178:179], v[82:83], s[38:39], v[176:177] op_sel_hi:[1,0,0]
	v_pk_fma_f32 v[174:175], v[84:85], s[38:39], v[176:177] op_sel_hi:[1,0,0]
	v_pk_fma_f32 v[172:173], v[86:87], s[38:39], v[176:177] op_sel_hi:[1,0,0]
	v_pk_fma_f32 v[170:171], v[88:89], s[38:39], v[176:177] op_sel_hi:[1,0,0]
	v_pk_fma_f32 v[168:169], v[90:91], s[38:39], v[176:177] op_sel_hi:[1,0,0]
	v_pk_fma_f32 v[166:167], v[92:93], s[38:39], v[176:177] op_sel_hi:[1,0,0]
	v_pk_fma_f32 v[164:165], v[94:95], s[38:39], v[176:177] op_sel_hi:[1,0,0]
	v_fmac_f32_e32 v201, v74, v222
	s_cmp_ge_u32 s17, s19
	s_waitcnt lgkmcnt(0)
	s_barrier
	s_cbranch_scc1 .LBB0_358
	s_mov_b32 s35, s16
	v_mov_b32_e32 v219, v177
	s_branch .LBB0_344

; DI bf16* xb_row(float* outp, int m) { return (bf16*)((char*)outp + (size_t)m * 8192 + 4096); }
; __global__ void __launch_bounds__(512) fwd_mega(Args a_) {
;     ...
;       } else {
;         for (int m = gw; m < MT; m += NGW)
;           row_resid_norm<true, true>((const bf16*)(ws + A_T) + (size_t)m * DM, tail8 ? (const bf16*)(ws + A_PF) + (size_t)(m - NPR) * DM : (const bf16*)(ws + A_H) + (size_t)m * DM, tail8 ? (m < NPR ? 0 : 8) : 1, xb_row(outp, m), xb_row(outp, m), a.in[9], (float*)(ws + A_RSTD) + m, lane);
.LBB0_371:
	s_and_b64 vcc, exec, s[46:47]
	s_cbranch_vccz .LBB0_451
	v_readlane_b32 s0, v255, 35
	s_cmp_eq_u32 s0, 0
	s_cbranch_scc1 .LBB0_429
	s_cmpk_gt_i32 s72, 0x43ff
	s_cbranch_scc1 .LBB0_428
	s_and_b64 vcc, exec, s[78:79]
	s_cbranch_vccz .Lrp_orig7
	s_load_dwordx2 s[6:7], s[22:23], 0x48
	s_mov_b32 s10, 0x21000000
	s_mov_b32 s11, 2
	s_waitcnt lgkmcnt(0)
	s_branch .Lrp_entry
.Lrp_orig7:
	s_load_dwordx2 s[2:3], s[22:23], 0x48
	v_lshlrev_b32_e32 v112, 4, v186
	s_add_u32 s0, s54, 0x21000000
	s_addc_u32 s1, s55, 0
	s_ashr_i32 s73, s72, 31
	s_waitcnt lgkmcnt(0)
	v_lshl_add_u64 v[4:5], s[2:3], 0, v[112:113]
	s_mov_b64 s[2:3], 0x1000
	v_lshl_add_u64 v[6:7], v[4:5], 0, s[2:3]
	s_mov_b64 s[2:3], 0x1400
	v_lshl_add_u64 v[8:9], v[4:5], 0, s[2:3]
	s_mov_b64 s[2:3], 0x1800
	v_lshl_add_u64 v[10:11], v[4:5], 0, s[2:3]
	s_mov_b64 s[2:3], 0x1c00
	v_lshl_add_u64 v[12:13], v[4:5], 0, s[2:3]
	s_lshl_b64 s[2:3], s[72:73], 13
	s_add_u32 s6, s52, s2
	s_addc_u32 s7, s53, s3
	s_lshl_b64 s[2:3], s[72:73], 2
	s_add_u32 s8, s96, s2
	s_addc_u32 s9, s97, s3
	s_lshl_b64 s[2:3], s[72:73], 12
	s_add_u32 s2, s54, s2
	s_addc_u32 s3, s55, s3
	s_add_u32 s10, s2, 0x7400000
	v_cmp_eq_u32_e64 s[42:43], 0, v186
	v_lshlrev_b32_e32 v14, 3, v186
	v_mov_b32_e32 v15, v113
	s_addc_u32 s11, s3, 0
	v_lshlrev_b32_e32 v112, 3, v186
	s_mov_b32 s2, s72
	s_branch .LBB0_376
